# GEMM K-loop heads aligned to 64 bytes (code placement) on top of scan + xattn fixes
# baseline (speedup 1.0000x reference)
; template <class Epi, class Sched, bool ALIGN_EPI = false>
; __device__ __forceinline__ void gemm_phase(PG8_LAS unsigned char* lds, const Gemm g, const Sched& S, const Epi& E) {
;     ...
;         const bool has_next = S.next(ui + 1, nxt);
;         const char* nA = has_next ? (const char*)g.A + (size_t)nxt.pm * tstepA : cA; const char* nB = has_next ? (const char*)g.Bt + (size_t)nxt.pn * tstepB : cB;
;         for (int t = 0; t < nt; t += 2) {
;             const bool last = (t == nt - 2);
;             const char* a1 = cA + (size_t)(t + 1) * kstep;
;             const char* a2 = last ? nA : cA + (size_t)(t + 2) * kstep; const char* b2 = last ? nB : cB + (size_t)(t + 2) * kstep;
;             const char* a3 = a2 + kstep; const char* b3 = b2 + kstep;
;     ...
; #pragma unroll
;         for (int a = 0; a < 2; ++a)
; #pragma unroll
;             for (int b = 0; b < 2; ++b)
; #pragma unroll
;                 for (int m = 0; m < 4; ++m)
; #pragma unroll
;                     for (int n = 0; n < 2; ++n) acc[a][b][m][n] = (f32x4){0.f, 0.f, 0.f, 0.f};
;         cur = nxt; cA = nA; cB = nB; ++ui;
.LBB0_197:
	s_ashr_i32 s35, s34, 31
	s_lshl_b64 s[36:37], s[34:35], 21
	s_add_u32 s36, s42, s36
	s_addc_u32 s37, s43, s37
	s_and_b64 s[38:39], s[2:3], exec
	s_cselect_b32 s5, s37, s7
	s_cselect_b32 s14, s36, s6
	s_ashr_i32 s31, s30, 31
	s_lshl_b64 s[38:39], s[30:31], 21
	s_add_u32 s38, s44, s38
	s_addc_u32 s39, s45, s39
	s_and_b64 s[40:41], s[2:3], exec
	s_cselect_b32 s31, s39, s9
	s_cselect_b32 s35, s38, s8
	s_add_u32 s6, s6, 0x100080
	s_addc_u32 s7, s7, 0
	s_add_u32 s61, s8, 0x100
	v_mov_b32_e32 v2, 0
	s_addc_u32 s62, s9, 0
	s_mov_b32 s63, -2
	v_mov_b32_e32 v3, v2
	v_mov_b32_e32 v4, v2
	v_mov_b32_e32 v5, v2
	v_mov_b32_e32 v6, v2
	v_mov_b32_e32 v7, v2
	v_mov_b32_e32 v8, v2
	v_mov_b32_e32 v9, v2
	v_mov_b32_e32 v18, v2
	v_mov_b32_e32 v19, v2
	v_mov_b32_e32 v20, v2
	v_mov_b32_e32 v21, v2
	v_mov_b32_e32 v22, v2
	v_mov_b32_e32 v23, v2
	v_mov_b32_e32 v24, v2
	v_mov_b32_e32 v25, v2
	v_mov_b32_e32 v34, v2
	v_mov_b32_e32 v35, v2
	v_mov_b32_e32 v36, v2
	v_mov_b32_e32 v37, v2
	v_mov_b32_e32 v38, v2
	v_mov_b32_e32 v39, v2
	v_mov_b32_e32 v40, v2
	v_mov_b32_e32 v41, v2
	v_mov_b32_e32 v66, v2
	v_mov_b32_e32 v67, v2
	v_mov_b32_e32 v68, v2
	v_mov_b32_e32 v69, v2
	v_mov_b32_e32 v70, v2
	v_mov_b32_e32 v71, v2
	v_mov_b32_e32 v72, v2
	v_mov_b32_e32 v73, v2
	v_mov_b32_e32 v10, v2
	v_mov_b32_e32 v11, v2
	v_mov_b32_e32 v12, v2
	v_mov_b32_e32 v13, v2
	v_mov_b32_e32 v14, v2
	v_mov_b32_e32 v15, v2
	v_mov_b32_e32 v16, v2
	v_mov_b32_e32 v17, v2
	v_mov_b32_e32 v26, v2
	v_mov_b32_e32 v27, v2
	v_mov_b32_e32 v28, v2
	v_mov_b32_e32 v29, v2
	v_mov_b32_e32 v30, v2
	v_mov_b32_e32 v31, v2
	v_mov_b32_e32 v32, v2
	v_mov_b32_e32 v33, v2
	v_mov_b32_e32 v54, v2
	v_mov_b32_e32 v55, v2
	v_mov_b32_e32 v56, v2
	v_mov_b32_e32 v57, v2
	v_mov_b32_e32 v62, v2
	v_mov_b32_e32 v63, v2
	v_mov_b32_e32 v64, v2
	v_mov_b32_e32 v65, v2
	v_mov_b32_e32 v74, v2
	v_mov_b32_e32 v75, v2
	v_mov_b32_e32 v76, v2
	v_mov_b32_e32 v77, v2
	v_mov_b32_e32 v78, v2
	v_mov_b32_e32 v79, v2
	v_mov_b32_e32 v80, v2
	v_mov_b32_e32 v81, v2
	v_mov_b32_e32 v82, v2
	v_mov_b32_e32 v83, v2
	v_mov_b32_e32 v84, v2
	v_mov_b32_e32 v85, v2
	v_mov_b32_e32 v86, v2
	v_mov_b32_e32 v87, v2
	v_mov_b32_e32 v88, v2
	v_mov_b32_e32 v89, v2
	v_mov_b32_e32 v98, v2
	v_mov_b32_e32 v99, v2
	v_mov_b32_e32 v100, v2
	v_mov_b32_e32 v101, v2
	v_mov_b32_e32 v102, v2
	v_mov_b32_e32 v103, v2
	v_mov_b32_e32 v104, v2
	v_mov_b32_e32 v105, v2
	v_mov_b32_e32 v114, v2
	v_mov_b32_e32 v115, v2
	v_mov_b32_e32 v116, v2
	v_mov_b32_e32 v117, v2
	v_mov_b32_e32 v118, v2
	v_mov_b32_e32 v119, v2
	v_mov_b32_e32 v120, v2
	v_mov_b32_e32 v121, v2
	v_mov_b32_e32 v130, v2
	v_mov_b32_e32 v131, v2
	v_mov_b32_e32 v132, v2
	v_mov_b32_e32 v133, v2
	v_mov_b32_e32 v134, v2
	v_mov_b32_e32 v135, v2
	v_mov_b32_e32 v136, v2
	v_mov_b32_e32 v137, v2
	v_mov_b32_e32 v90, v2
	v_mov_b32_e32 v91, v2
	v_mov_b32_e32 v92, v2
	v_mov_b32_e32 v93, v2
	v_mov_b32_e32 v94, v2
	v_mov_b32_e32 v95, v2
	v_mov_b32_e32 v96, v2
	v_mov_b32_e32 v97, v2
	v_mov_b32_e32 v106, v2
	v_mov_b32_e32 v107, v2
	v_mov_b32_e32 v108, v2
	v_mov_b32_e32 v109, v2
	v_mov_b32_e32 v110, v2
	v_mov_b32_e32 v111, v2
	v_mov_b32_e32 v112, v2
	v_mov_b32_e32 v113, v2
	v_mov_b32_e32 v122, v2
	v_mov_b32_e32 v123, v2
	v_mov_b32_e32 v124, v2
	v_mov_b32_e32 v125, v2
	v_mov_b32_e32 v126, v2
	v_mov_b32_e32 v127, v2
	v_mov_b32_e32 v128, v2
	v_mov_b32_e32 v129, v2
	v_mov_b32_e32 v138, v2
	v_mov_b32_e32 v139, v2
	v_mov_b32_e32 v140, v2
	v_mov_b32_e32 v141, v2
	v_mov_b32_e32 v142, v2
	v_mov_b32_e32 v143, v2
	v_mov_b32_e32 v144, v2
	v_mov_b32_e32 v145, v2
	.p2align	6

; template <class Epi, class Sched, bool ALIGN_EPI = false>
; __device__ __forceinline__ void gemm_phase(PG8_LAS unsigned char* lds, const Gemm g, const Sched& S, const Epi& E) {
;     ...
;         const bool has_next = S.next(ui + 1, nxt);
;         const char* nA = has_next ? (const char*)g.A + (size_t)nxt.pm * tstepA : cA; const char* nB = has_next ? (const char*)g.Bt + (size_t)nxt.pn * tstepB : cB;
;         for (int t = 0; t < nt; t += 2) {
;             const bool last = (t == nt - 2);
;             const char* a1 = cA + (size_t)(t + 1) * kstep;
;             const char* a2 = last ? nA : cA + (size_t)(t + 2) * kstep; const char* b2 = last ? nB : cB + (size_t)(t + 2) * kstep;
;             const char* a3 = a2 + kstep; const char* b3 = b2 + kstep;
;     ...
; #pragma unroll
;         for (int a = 0; a < 2; ++a)
; #pragma unroll
;             for (int b = 0; b < 2; ++b)
; #pragma unroll
;                 for (int m = 0; m < 4; ++m)
; #pragma unroll
;                     for (int n = 0; n < 2; ++n) acc[a][b][m][n] = (f32x4){0.f, 0.f, 0.f, 0.f};
;         cur = nxt; cA = nA; cB = nB; ++ui;
.LBB0_392:
	s_ashr_i32 s25, s24, 31
	s_lshl_b64 s[26:27], s[24:25], 21
	s_add_u32 s26, s1, s26
	s_addc_u32 s27, s40, s27
	s_and_b64 s[28:29], s[20:21], exec
	s_cselect_b32 s25, s27, s35
	s_cselect_b32 s62, s26, s34
	s_ashr_i32 s23, s22, 31
	s_lshl_b64 s[28:29], s[22:23], 21
	s_add_u32 s28, s41, s28
	s_addc_u32 s29, s42, s29
	s_and_b64 s[38:39], s[20:21], exec
	s_cselect_b32 s23, s29, s37
	s_cselect_b32 s63, s28, s36
	s_add_u32 s34, s34, 0x100080
	s_addc_u32 s35, s35, 0
	s_add_u32 s64, s36, 0x100
	v_mov_b32_e32 v2, 0
	s_addc_u32 s65, s37, 0
	s_mov_b32 s66, -2
	v_mov_b32_e32 v3, v2
	v_mov_b32_e32 v4, v2
	v_mov_b32_e32 v5, v2
	v_mov_b32_e32 v6, v2
	v_mov_b32_e32 v7, v2
	v_mov_b32_e32 v8, v2
	v_mov_b32_e32 v9, v2
	v_mov_b32_e32 v10, v2
	v_mov_b32_e32 v11, v2
	v_mov_b32_e32 v12, v2
	v_mov_b32_e32 v13, v2
	v_mov_b32_e32 v18, v2
	v_mov_b32_e32 v19, v2
	v_mov_b32_e32 v20, v2
	v_mov_b32_e32 v21, v2
	v_mov_b32_e32 v26, v2
	v_mov_b32_e32 v27, v2
	v_mov_b32_e32 v28, v2
	v_mov_b32_e32 v29, v2
	v_mov_b32_e32 v34, v2
	v_mov_b32_e32 v35, v2
	v_mov_b32_e32 v36, v2
	v_mov_b32_e32 v37, v2
	v_mov_b32_e32 v42, v2
	v_mov_b32_e32 v43, v2
	v_mov_b32_e32 v44, v2
	v_mov_b32_e32 v45, v2
	v_mov_b32_e32 v50, v2
	v_mov_b32_e32 v51, v2
	v_mov_b32_e32 v52, v2
	v_mov_b32_e32 v53, v2
	v_mov_b32_e32 v14, v2
	v_mov_b32_e32 v15, v2
	v_mov_b32_e32 v16, v2
	v_mov_b32_e32 v17, v2
	v_mov_b32_e32 v22, v2
	v_mov_b32_e32 v23, v2
	v_mov_b32_e32 v24, v2
	v_mov_b32_e32 v25, v2
	v_mov_b32_e32 v30, v2
	v_mov_b32_e32 v31, v2
	v_mov_b32_e32 v32, v2
	v_mov_b32_e32 v33, v2
	v_mov_b32_e32 v38, v2
	v_mov_b32_e32 v39, v2
	v_mov_b32_e32 v40, v2
	v_mov_b32_e32 v41, v2
	v_mov_b32_e32 v46, v2
	v_mov_b32_e32 v47, v2
	v_mov_b32_e32 v48, v2
	v_mov_b32_e32 v49, v2
	v_mov_b32_e32 v54, v2
	v_mov_b32_e32 v55, v2
	v_mov_b32_e32 v56, v2
	v_mov_b32_e32 v57, v2
	v_mov_b32_e32 v58, v2
	v_mov_b32_e32 v59, v2
	v_mov_b32_e32 v60, v2
	v_mov_b32_e32 v61, v2
	v_mov_b32_e32 v62, v2
	v_mov_b32_e32 v63, v2
	v_mov_b32_e32 v64, v2
	v_mov_b32_e32 v65, v2
	v_mov_b32_e32 v66, v2
	v_mov_b32_e32 v67, v2
	v_mov_b32_e32 v68, v2
	v_mov_b32_e32 v69, v2
	v_mov_b32_e32 v70, v2
	v_mov_b32_e32 v71, v2
	v_mov_b32_e32 v72, v2
	v_mov_b32_e32 v73, v2
	v_mov_b32_e32 v74, v2
	v_mov_b32_e32 v75, v2
	v_mov_b32_e32 v76, v2
	v_mov_b32_e32 v77, v2
	v_mov_b32_e32 v82, v2
	v_mov_b32_e32 v83, v2
	v_mov_b32_e32 v84, v2
	v_mov_b32_e32 v85, v2
	v_mov_b32_e32 v90, v2
	v_mov_b32_e32 v91, v2
	v_mov_b32_e32 v92, v2
	v_mov_b32_e32 v93, v2
	v_mov_b32_e32 v98, v2
	v_mov_b32_e32 v99, v2
	v_mov_b32_e32 v100, v2
	v_mov_b32_e32 v101, v2
	v_mov_b32_e32 v106, v2
	v_mov_b32_e32 v107, v2
	v_mov_b32_e32 v108, v2
	v_mov_b32_e32 v109, v2
	v_mov_b32_e32 v114, v2
	v_mov_b32_e32 v115, v2
	v_mov_b32_e32 v116, v2
	v_mov_b32_e32 v117, v2
	v_mov_b32_e32 v78, v2
	v_mov_b32_e32 v79, v2
	v_mov_b32_e32 v80, v2
	v_mov_b32_e32 v81, v2
	v_mov_b32_e32 v86, v2
	v_mov_b32_e32 v87, v2
	v_mov_b32_e32 v88, v2
	v_mov_b32_e32 v89, v2
	v_mov_b32_e32 v94, v2
	v_mov_b32_e32 v95, v2
	v_mov_b32_e32 v96, v2
	v_mov_b32_e32 v97, v2
	v_mov_b32_e32 v102, v2
	v_mov_b32_e32 v103, v2
	v_mov_b32_e32 v104, v2
	v_mov_b32_e32 v105, v2
	v_mov_b32_e32 v110, v2
	v_mov_b32_e32 v111, v2
	v_mov_b32_e32 v112, v2
	v_mov_b32_e32 v113, v2
	v_mov_b32_e32 v118, v2
	v_mov_b32_e32 v119, v2
	v_mov_b32_e32 v120, v2
	v_mov_b32_e32 v121, v2
	v_mov_b32_e32 v122, v2
	v_mov_b32_e32 v123, v2
	v_mov_b32_e32 v124, v2
	v_mov_b32_e32 v125, v2
	v_mov_b32_e32 v126, v2
	v_mov_b32_e32 v127, v2
	v_mov_b32_e32 v128, v2
	v_mov_b32_e32 v129, v2
	.p2align	6

; template <class Epi, class Sched, bool ALIGN_EPI = false>
; __device__ __forceinline__ void gemm_phase(PG8_LAS unsigned char* lds, const Gemm g, const Sched& S, const Epi& E) {
;     ...
;         const bool has_next = S.next(ui + 1, nxt);
;         const char* nA = has_next ? (const char*)g.A + (size_t)nxt.pm * tstepA : cA; const char* nB = has_next ? (const char*)g.Bt + (size_t)nxt.pn * tstepB : cB;
;         for (int t = 0; t < nt; t += 2) {
;             const bool last = (t == nt - 2);
;             const char* a1 = cA + (size_t)(t + 1) * kstep;
;             const char* a2 = last ? nA : cA + (size_t)(t + 2) * kstep; const char* b2 = last ? nB : cB + (size_t)(t + 2) * kstep;
;             const char* a3 = a2 + kstep; const char* b3 = b2 + kstep;
;     ...
; #pragma unroll
;         for (int a = 0; a < 2; ++a)
; #pragma unroll
;             for (int b = 0; b < 2; ++b)
; #pragma unroll
;                 for (int m = 0; m < 4; ++m)
; #pragma unroll
;                     for (int n = 0; n < 2; ++n) acc[a][b][m][n] = (f32x4){0.f, 0.f, 0.f, 0.f};
;         cur = nxt; cA = nA; cB = nB; ++ui;
.LBB0_534:
	s_ashr_i32 s27, s26, 31
	s_lshl_b64 s[28:29], s[26:27], 20
	s_add_u32 s28, s1, s28
	s_addc_u32 s29, s42, s29
	s_and_b64 s[30:31], s[2:3], exec
	s_cselect_b32 s27, s29, s37
	s_cselect_b32 s60, s28, s36
	s_ashr_i32 s25, s24, 31
	s_lshl_b64 s[30:31], s[24:25], 20
	s_add_u32 s30, s43, s30
	s_addc_u32 s31, s44, s31
	s_and_b64 s[40:41], s[2:3], exec
	s_cselect_b32 s25, s31, s39
	s_cselect_b32 s61, s30, s38
	s_add_u32 s36, s36, 0x80080
	s_addc_u32 s37, s37, 0
	s_add_u32 s62, s38, 0x100
	v_mov_b32_e32 v2, 0
	s_addc_u32 s63, s39, 0
	s_mov_b32 s64, -2
	v_mov_b32_e32 v3, v2
	v_mov_b32_e32 v4, v2
	v_mov_b32_e32 v5, v2
	v_mov_b32_e32 v6, v2
	v_mov_b32_e32 v7, v2
	v_mov_b32_e32 v8, v2
	v_mov_b32_e32 v9, v2
	v_mov_b32_e32 v18, v2
	v_mov_b32_e32 v19, v2
	v_mov_b32_e32 v20, v2
	v_mov_b32_e32 v21, v2
	v_mov_b32_e32 v22, v2
	v_mov_b32_e32 v23, v2
	v_mov_b32_e32 v24, v2
	v_mov_b32_e32 v25, v2
	v_mov_b32_e32 v34, v2
	v_mov_b32_e32 v35, v2
	v_mov_b32_e32 v36, v2
	v_mov_b32_e32 v37, v2
	v_mov_b32_e32 v38, v2
	v_mov_b32_e32 v39, v2
	v_mov_b32_e32 v40, v2
	v_mov_b32_e32 v41, v2
	s_waitcnt vmcnt(0)
	v_mov_b32_e32 v50, v2
	v_mov_b32_e32 v51, v2
	v_mov_b32_e32 v52, v2
	v_mov_b32_e32 v53, v2
	v_mov_b32_e32 v54, v2
	v_mov_b32_e32 v55, v2
	v_mov_b32_e32 v56, v2
	v_mov_b32_e32 v57, v2
	v_mov_b32_e32 v10, v2
	v_mov_b32_e32 v11, v2
	v_mov_b32_e32 v12, v2
	v_mov_b32_e32 v13, v2
	v_mov_b32_e32 v14, v2
	v_mov_b32_e32 v15, v2
	v_mov_b32_e32 v16, v2
	v_mov_b32_e32 v17, v2
	v_mov_b32_e32 v26, v2
	v_mov_b32_e32 v27, v2
	v_mov_b32_e32 v28, v2
	v_mov_b32_e32 v29, v2
	v_mov_b32_e32 v30, v2
	v_mov_b32_e32 v31, v2
	v_mov_b32_e32 v32, v2
	v_mov_b32_e32 v33, v2
	v_mov_b32_e32 v42, v2
	v_mov_b32_e32 v43, v2
	v_mov_b32_e32 v44, v2
	v_mov_b32_e32 v45, v2
	v_mov_b32_e32 v46, v2
	v_mov_b32_e32 v47, v2
	v_mov_b32_e32 v48, v2
	v_mov_b32_e32 v49, v2
	v_mov_b32_e32 v58, v2
	v_mov_b32_e32 v59, v2
	v_mov_b32_e32 v60, v2
	v_mov_b32_e32 v61, v2
	v_mov_b32_e32 v62, v2
	v_mov_b32_e32 v63, v2
	v_mov_b32_e32 v64, v2
	v_mov_b32_e32 v65, v2
	v_mov_b32_e32 v66, v2
	v_mov_b32_e32 v67, v2
	v_mov_b32_e32 v68, v2
	v_mov_b32_e32 v69, v2
	v_mov_b32_e32 v70, v2
	v_mov_b32_e32 v71, v2
	v_mov_b32_e32 v72, v2
	v_mov_b32_e32 v73, v2
	v_mov_b32_e32 v82, v2
	v_mov_b32_e32 v83, v2
	v_mov_b32_e32 v84, v2
	v_mov_b32_e32 v85, v2
	v_mov_b32_e32 v86, v2
	v_mov_b32_e32 v87, v2
	v_mov_b32_e32 v88, v2
	v_mov_b32_e32 v89, v2
	v_mov_b32_e32 v98, v2
	v_mov_b32_e32 v99, v2
	v_mov_b32_e32 v100, v2
	v_mov_b32_e32 v101, v2
	v_mov_b32_e32 v102, v2
	v_mov_b32_e32 v103, v2
	v_mov_b32_e32 v104, v2
	v_mov_b32_e32 v105, v2
	v_mov_b32_e32 v114, v2
	v_mov_b32_e32 v115, v2
	v_mov_b32_e32 v116, v2
	v_mov_b32_e32 v117, v2
	v_mov_b32_e32 v118, v2
	v_mov_b32_e32 v119, v2
	v_mov_b32_e32 v120, v2
	v_mov_b32_e32 v121, v2
	v_mov_b32_e32 v74, v2
	v_mov_b32_e32 v75, v2
	v_mov_b32_e32 v76, v2
	v_mov_b32_e32 v77, v2
	v_mov_b32_e32 v78, v2
	v_mov_b32_e32 v79, v2
	v_mov_b32_e32 v80, v2
	v_mov_b32_e32 v81, v2
	v_mov_b32_e32 v90, v2
	v_mov_b32_e32 v91, v2
	v_mov_b32_e32 v92, v2
	v_mov_b32_e32 v93, v2
	v_mov_b32_e32 v94, v2
	v_mov_b32_e32 v95, v2
	v_mov_b32_e32 v96, v2
	v_mov_b32_e32 v97, v2
	v_mov_b32_e32 v106, v2
	v_mov_b32_e32 v107, v2
	v_mov_b32_e32 v108, v2
	v_mov_b32_e32 v109, v2
	v_mov_b32_e32 v110, v2
	v_mov_b32_e32 v111, v2
	v_mov_b32_e32 v112, v2
	v_mov_b32_e32 v113, v2
	v_mov_b32_e32 v122, v2
	v_mov_b32_e32 v123, v2
	v_mov_b32_e32 v124, v2
	v_mov_b32_e32 v125, v2
	v_mov_b32_e32 v126, v2
	v_mov_b32_e32 v127, v2
	v_mov_b32_e32 v128, v2
	v_mov_b32_e32 v129, v2
	.p2align	6

; template <class Epi, class Sched, bool ALIGN_EPI = false>
; __device__ __forceinline__ void gemm_phase(PG8_LAS unsigned char* lds, const Gemm g, const Sched& S, const Epi& E) {
;     ...
;         const bool has_next = S.next(ui + 1, nxt);
;         const char* nA = has_next ? (const char*)g.A + (size_t)nxt.pm * tstepA : cA; const char* nB = has_next ? (const char*)g.Bt + (size_t)nxt.pn * tstepB : cB;
;         for (int t = 0; t < nt; t += 2) {
;             const bool last = (t == nt - 2);
;             const char* a1 = cA + (size_t)(t + 1) * kstep;
;             const char* a2 = last ? nA : cA + (size_t)(t + 2) * kstep; const char* b2 = last ? nB : cB + (size_t)(t + 2) * kstep;
;             const char* a3 = a2 + kstep; const char* b3 = b2 + kstep;
;     ...
; #pragma unroll
;         for (int a = 0; a < 2; ++a)
; #pragma unroll
;             for (int b = 0; b < 2; ++b)
; #pragma unroll
;                 for (int m = 0; m < 4; ++m)
; #pragma unroll
;                     for (int n = 0; n < 2; ++n) acc[a][b][m][n] = (f32x4){0.f, 0.f, 0.f, 0.f};
;         cur = nxt; cA = nA; cB = nB; ++ui;
;     __device__ __forceinline__ void operator()(const f32x4 (&acc)[2][2][4][2], const Unit& u, int, int, int, int) const {
;     ...
;                 const f32x4 w0 = *(const f32x4*)(cw + c0 + 4 * n), w1 = *(const f32x4*)(cw + DFF + c0 + 4 * n), w2 = *(const f32x4*)(cw + 2 * DFF + c0 + 4 * n), bb = *(const f32x4*)(cb + c0 + 4 * n);
.LBB0_655:
	s_ashr_i32 s43, s42, 31
	s_lshl_b64 s[44:45], s[42:43], 21
	s_add_u32 s44, s0, s44
	s_addc_u32 s45, s1, s45
	s_and_b64 s[46:47], s[2:3], exec
	s_cselect_b32 s43, s45, s5
	s_cselect_b32 s50, s44, s4
	s_ashr_i32 s41, s40, 31
	s_lshl_b64 s[46:47], s[40:41], 21
	s_add_u32 s46, s52, s46
	s_addc_u32 s47, s53, s47
	s_and_b64 s[48:49], s[2:3], exec
	s_cselect_b32 s41, s47, s7
	s_cselect_b32 s51, s46, s6
	s_add_u32 s4, s4, 0x100080
	s_addc_u32 s5, s5, 0
	s_add_u32 s74, s6, 0x100
	v_mov_b32_e32 v18, 0
	s_addc_u32 s75, s7, 0
	s_mov_b32 s76, -2
	v_mov_b32_e32 v19, v18
	v_mov_b32_e32 v20, v18
	v_mov_b32_e32 v21, v18
	s_lshl_b32 s98, s9, 7
	v_readfirstlane_b32 s99, v0
	s_nop 3
	s_lshr_b32 s99, s99, 1
	s_and_b32 s99, s99, 0x60
	s_or_b32 s98, s99, s98
	v_lshrrev_b32_e32 v250, 1, v0
	v_and_or_b32 v250, v250, 24, s98
	v_lshlrev_b32_e32 v250, 2, v250
	global_load_dwordx4 v[216:219], v250, s[12:13]
	global_load_dwordx4 v[220:223], v250, s[14:15]
	global_load_dwordx4 v[224:227], v250, s[26:27]
	global_load_dwordx4 v[230:233], v250, s[28:29]
	global_load_dwordx4 v[234:237], v250, s[12:13] offset:16
	global_load_dwordx4 v[238:241], v250, s[14:15] offset:16
	global_load_dwordx4 v[242:245], v250, s[26:27] offset:16
	global_load_dwordx4 v[246:249], v250, s[28:29] offset:16
	s_waitcnt vmcnt(0)
	v_mov_b32_e32 v46, v18
	v_mov_b32_e32 v47, v18
	v_mov_b32_e32 v48, v18
	v_mov_b32_e32 v49, v18
	v_mov_b32_e32 v30, v18
	v_mov_b32_e32 v31, v18
	v_mov_b32_e32 v32, v18
	v_mov_b32_e32 v33, v18
	v_mov_b32_e32 v50, v18
	v_mov_b32_e32 v51, v18
	v_mov_b32_e32 v52, v18
	v_mov_b32_e32 v53, v18
	v_mov_b32_e32 v34, v18
	v_mov_b32_e32 v35, v18
	v_mov_b32_e32 v36, v18
	v_mov_b32_e32 v37, v18
	v_mov_b32_e32 v54, v18
	v_mov_b32_e32 v55, v18
	v_mov_b32_e32 v56, v18
	v_mov_b32_e32 v57, v18
	v_mov_b32_e32 v10, v18
	v_mov_b32_e32 v11, v18
	v_mov_b32_e32 v12, v18
	v_mov_b32_e32 v13, v18
	v_mov_b32_e32 v14, v18
	v_mov_b32_e32 v15, v18
	v_mov_b32_e32 v16, v18
	v_mov_b32_e32 v17, v18
	v_mov_b32_e32 v2, v18
	v_mov_b32_e32 v3, v18
	v_mov_b32_e32 v4, v18
	v_mov_b32_e32 v5, v18
	v_mov_b32_e32 v6, v18
	v_mov_b32_e32 v7, v18
	v_mov_b32_e32 v8, v18
	v_mov_b32_e32 v9, v18
	v_mov_b32_e32 v38, v18
	v_mov_b32_e32 v39, v18
	v_mov_b32_e32 v40, v18
	v_mov_b32_e32 v41, v18
	v_mov_b32_e32 v58, v18
	v_mov_b32_e32 v59, v18
	v_mov_b32_e32 v60, v18
	v_mov_b32_e32 v61, v18
	v_mov_b32_e32 v42, v18
	v_mov_b32_e32 v43, v18
	v_mov_b32_e32 v44, v18
	v_mov_b32_e32 v45, v18
	v_mov_b32_e32 v62, v18
	v_mov_b32_e32 v63, v18
	v_mov_b32_e32 v64, v18
	v_mov_b32_e32 v65, v18
	v_mov_b32_e32 v22, v18
	v_mov_b32_e32 v23, v18
	v_mov_b32_e32 v24, v18
	v_mov_b32_e32 v25, v18
	v_mov_b32_e32 v26, v18
	v_mov_b32_e32 v27, v18
	v_mov_b32_e32 v28, v18
	v_mov_b32_e32 v29, v18
	v_mov_b32_e32 v82, v18
	v_mov_b32_e32 v83, v18
	v_mov_b32_e32 v84, v18
	v_mov_b32_e32 v85, v18
	v_mov_b32_e32 v110, v18
	v_mov_b32_e32 v111, v18
	v_mov_b32_e32 v112, v18
	v_mov_b32_e32 v113, v18
	v_mov_b32_e32 v94, v18
	v_mov_b32_e32 v95, v18
	v_mov_b32_e32 v96, v18
	v_mov_b32_e32 v97, v18
	v_mov_b32_e32 v114, v18
	v_mov_b32_e32 v115, v18
	v_mov_b32_e32 v116, v18
	v_mov_b32_e32 v117, v18
	v_mov_b32_e32 v98, v18
	v_mov_b32_e32 v99, v18
	v_mov_b32_e32 v100, v18
	v_mov_b32_e32 v101, v18
	v_mov_b32_e32 v118, v18
	v_mov_b32_e32 v119, v18
	v_mov_b32_e32 v120, v18
	v_mov_b32_e32 v121, v18
	v_mov_b32_e32 v74, v18
	v_mov_b32_e32 v75, v18
	v_mov_b32_e32 v76, v18
	v_mov_b32_e32 v77, v18
	v_mov_b32_e32 v78, v18
	v_mov_b32_e32 v79, v18
	v_mov_b32_e32 v80, v18
	v_mov_b32_e32 v81, v18
	v_mov_b32_e32 v66, v18
	v_mov_b32_e32 v67, v18
	v_mov_b32_e32 v68, v18
	v_mov_b32_e32 v69, v18
	v_mov_b32_e32 v70, v18
	v_mov_b32_e32 v71, v18
	v_mov_b32_e32 v72, v18
	v_mov_b32_e32 v73, v18
	v_mov_b32_e32 v102, v18
	v_mov_b32_e32 v103, v18
	v_mov_b32_e32 v104, v18
	v_mov_b32_e32 v105, v18
	v_mov_b32_e32 v122, v18
	v_mov_b32_e32 v123, v18
	v_mov_b32_e32 v124, v18
	v_mov_b32_e32 v125, v18
	v_mov_b32_e32 v106, v18
	v_mov_b32_e32 v107, v18
	v_mov_b32_e32 v108, v18
	v_mov_b32_e32 v109, v18
	v_mov_b32_e32 v126, v18
	v_mov_b32_e32 v127, v18
	v_mov_b32_e32 v128, v18
	v_mov_b32_e32 v129, v18
	v_mov_b32_e32 v86, v18
	v_mov_b32_e32 v87, v18
	v_mov_b32_e32 v88, v18
	v_mov_b32_e32 v89, v18
	v_mov_b32_e32 v90, v18
	v_mov_b32_e32 v91, v18
	v_mov_b32_e32 v92, v18
	v_mov_b32_e32 v93, v18
	.p2align	6

; template <class Epi, class Sched, bool ALIGN_EPI = false>
; __device__ __forceinline__ void gemm_phase(PG8_LAS unsigned char* lds, const Gemm g, const Sched& S, const Epi& E) {
;     ...
;             const char* a3 = a2 + kstep; const char* b3 = b2 + kstep;
;     ...
; #pragma unroll
;         for (int a = 0; a < 2; ++a)
; #pragma unroll
;             for (int b = 0; b < 2; ++b)
; #pragma unroll
;                 for (int m = 0; m < 4; ++m)
; #pragma unroll
;                     for (int n = 0; n < 2; ++n) acc[a][b][m][n] = (f32x4){0.f, 0.f, 0.f, 0.f};
;         cur = nxt; cA = nA; cB = nB; ++ui;
.LBB0_811:
	s_add_u32 s62, s28, 0x100
	v_mov_b32_e32 v2, 0
	s_addc_u32 s63, s29, 0
	s_mov_b32 s64, -2
	v_mov_b32_e32 v3, v2
	v_mov_b32_e32 v4, v2
	v_mov_b32_e32 v5, v2
	v_mov_b32_e32 v6, v2
	v_mov_b32_e32 v7, v2
	v_mov_b32_e32 v8, v2
	v_mov_b32_e32 v9, v2
	v_mov_b32_e32 v14, v2
	v_mov_b32_e32 v15, v2
	v_mov_b32_e32 v16, v2
	v_mov_b32_e32 v17, v2
	v_mov_b32_e32 v22, v2
	v_mov_b32_e32 v23, v2
	v_mov_b32_e32 v24, v2
	v_mov_b32_e32 v25, v2
	v_mov_b32_e32 v30, v2
	v_mov_b32_e32 v31, v2
	v_mov_b32_e32 v32, v2
	v_mov_b32_e32 v33, v2
	v_mov_b32_e32 v38, v2
	v_mov_b32_e32 v39, v2
	v_mov_b32_e32 v40, v2
	v_mov_b32_e32 v41, v2
	s_waitcnt vmcnt(0)
	v_mov_b32_e32 v46, v2
	v_mov_b32_e32 v47, v2
	v_mov_b32_e32 v48, v2
	v_mov_b32_e32 v49, v2
	v_mov_b32_e32 v54, v2
	v_mov_b32_e32 v55, v2
	v_mov_b32_e32 v56, v2
	v_mov_b32_e32 v57, v2
	v_mov_b32_e32 v10, v2
	v_mov_b32_e32 v11, v2
	v_mov_b32_e32 v12, v2
	v_mov_b32_e32 v13, v2
	v_mov_b32_e32 v18, v2
	v_mov_b32_e32 v19, v2
	v_mov_b32_e32 v20, v2
	v_mov_b32_e32 v21, v2
	v_mov_b32_e32 v26, v2
	v_mov_b32_e32 v27, v2
	v_mov_b32_e32 v28, v2
	v_mov_b32_e32 v29, v2
	v_mov_b32_e32 v34, v2
	v_mov_b32_e32 v35, v2
	v_mov_b32_e32 v36, v2
	v_mov_b32_e32 v37, v2
	v_mov_b32_e32 v42, v2
	v_mov_b32_e32 v43, v2
	v_mov_b32_e32 v44, v2
	v_mov_b32_e32 v45, v2
	v_mov_b32_e32 v50, v2
	v_mov_b32_e32 v51, v2
	v_mov_b32_e32 v52, v2
	v_mov_b32_e32 v53, v2
	v_mov_b32_e32 v58, v2
	v_mov_b32_e32 v59, v2
	v_mov_b32_e32 v60, v2
	v_mov_b32_e32 v61, v2
	v_mov_b32_e32 v62, v2
	v_mov_b32_e32 v63, v2
	v_mov_b32_e32 v64, v2
	v_mov_b32_e32 v65, v2
	v_mov_b32_e32 v66, v2
	v_mov_b32_e32 v67, v2
	v_mov_b32_e32 v68, v2
	v_mov_b32_e32 v69, v2
	v_mov_b32_e32 v70, v2
	v_mov_b32_e32 v71, v2
	v_mov_b32_e32 v72, v2
	v_mov_b32_e32 v73, v2
	v_mov_b32_e32 v78, v2
	v_mov_b32_e32 v79, v2
	v_mov_b32_e32 v80, v2
	v_mov_b32_e32 v81, v2
	v_mov_b32_e32 v86, v2
	v_mov_b32_e32 v87, v2
	v_mov_b32_e32 v88, v2
	v_mov_b32_e32 v89, v2
	v_mov_b32_e32 v94, v2
	v_mov_b32_e32 v95, v2
	v_mov_b32_e32 v96, v2
	v_mov_b32_e32 v97, v2
	v_mov_b32_e32 v102, v2
	v_mov_b32_e32 v103, v2
	v_mov_b32_e32 v104, v2
	v_mov_b32_e32 v105, v2
	v_mov_b32_e32 v110, v2
	v_mov_b32_e32 v111, v2
	v_mov_b32_e32 v112, v2
	v_mov_b32_e32 v113, v2
	v_mov_b32_e32 v118, v2
	v_mov_b32_e32 v119, v2
	v_mov_b32_e32 v120, v2
	v_mov_b32_e32 v121, v2
	v_mov_b32_e32 v74, v2
	v_mov_b32_e32 v75, v2
	v_mov_b32_e32 v76, v2
	v_mov_b32_e32 v77, v2
	v_mov_b32_e32 v82, v2
	v_mov_b32_e32 v83, v2
	v_mov_b32_e32 v84, v2
	v_mov_b32_e32 v85, v2
	v_mov_b32_e32 v90, v2
	v_mov_b32_e32 v91, v2
	v_mov_b32_e32 v92, v2
	v_mov_b32_e32 v93, v2
	v_mov_b32_e32 v98, v2
	v_mov_b32_e32 v99, v2
	v_mov_b32_e32 v100, v2
	v_mov_b32_e32 v101, v2
	v_mov_b32_e32 v106, v2
	v_mov_b32_e32 v107, v2
	v_mov_b32_e32 v108, v2
	v_mov_b32_e32 v109, v2
	v_mov_b32_e32 v114, v2
	v_mov_b32_e32 v115, v2
	v_mov_b32_e32 v116, v2
	v_mov_b32_e32 v117, v2
	v_mov_b32_e32 v122, v2
	v_mov_b32_e32 v123, v2
	v_mov_b32_e32 v124, v2
	v_mov_b32_e32 v125, v2
	v_mov_b32_e32 v126, v2
	v_mov_b32_e32 v127, v2
	v_mov_b32_e32 v128, v2
	v_mov_b32_e32 v129, v2
	.p2align	6

; template <class Epi, class Sched, bool ALIGN_EPI = false>
; __device__ __forceinline__ void gemm_phase(PG8_LAS unsigned char* lds, const Gemm g, const Sched& S, const Epi& E) {
;     ...
;         const bool has_next = S.next(ui + 1, nxt);
;         const char* nA = has_next ? (const char*)g.A + (size_t)nxt.pm * tstepA : cA; const char* nB = has_next ? (const char*)g.Bt + (size_t)nxt.pn * tstepB : cB;
;         for (int t = 0; t < nt; t += 2) {
;             const bool last = (t == nt - 2);
;             const char* a1 = cA + (size_t)(t + 1) * kstep;
;             const char* a2 = last ? nA : cA + (size_t)(t + 2) * kstep; const char* b2 = last ? nB : cB + (size_t)(t + 2) * kstep;
;             const char* a3 = a2 + kstep; const char* b3 = b2 + kstep;
;     ...
; #pragma unroll
;         for (int a = 0; a < 2; ++a)
; #pragma unroll
;             for (int b = 0; b < 2; ++b)
; #pragma unroll
;                 for (int m = 0; m < 4; ++m)
; #pragma unroll
;                     for (int n = 0; n < 2; ++n) acc[a][b][m][n] = (f32x4){0.f, 0.f, 0.f, 0.f};
;         cur = nxt; cA = nA; cB = nB; ++ui;
.LBB0_932:
	s_ashr_i32 s17, s16, 31
	s_lshl_b64 s[18:19], s[16:17], 21
	s_add_u32 s18, s0, s18
	s_addc_u32 s19, s1, s19
	s_and_b64 s[20:21], s[2:3], exec
	s_cselect_b32 s17, s19, s25
	s_cselect_b32 s48, s18, s24
	s_ashr_i32 s15, s14, 31
	s_lshl_b64 s[20:21], s[14:15], 21
	s_add_u32 s20, s30, s20
	s_addc_u32 s21, s31, s21
	s_and_b64 s[28:29], s[2:3], exec
	s_cselect_b32 s15, s21, s27
	s_cselect_b32 s49, s20, s26
	s_add_u32 s24, s24, 0x100080
	s_addc_u32 s25, s25, 0
	s_add_u32 s50, s26, 0x100
	v_mov_b32_e32 v2, 0
	s_addc_u32 s51, s27, 0
	s_mov_b32 s52, -2
	v_mov_b32_e32 v3, v2
	v_mov_b32_e32 v4, v2
	v_mov_b32_e32 v5, v2
	v_mov_b32_e32 v6, v2
	v_mov_b32_e32 v7, v2
	v_mov_b32_e32 v8, v2
	v_mov_b32_e32 v9, v2
	v_mov_b32_e32 v10, v2
	v_mov_b32_e32 v11, v2
	v_mov_b32_e32 v12, v2
	v_mov_b32_e32 v13, v2
	v_mov_b32_e32 v18, v2
	v_mov_b32_e32 v19, v2
	v_mov_b32_e32 v20, v2
	v_mov_b32_e32 v21, v2
	v_mov_b32_e32 v26, v2
	v_mov_b32_e32 v27, v2
	v_mov_b32_e32 v28, v2
	v_mov_b32_e32 v29, v2
	v_mov_b32_e32 v34, v2
	v_mov_b32_e32 v35, v2
	v_mov_b32_e32 v36, v2
	v_mov_b32_e32 v37, v2
	v_mov_b32_e32 v42, v2
	v_mov_b32_e32 v43, v2
	v_mov_b32_e32 v44, v2
	v_mov_b32_e32 v45, v2
	v_mov_b32_e32 v50, v2
	v_mov_b32_e32 v51, v2
	v_mov_b32_e32 v52, v2
	v_mov_b32_e32 v53, v2
	v_mov_b32_e32 v14, v2
	v_mov_b32_e32 v15, v2
	v_mov_b32_e32 v16, v2
	v_mov_b32_e32 v17, v2
	v_mov_b32_e32 v22, v2
	v_mov_b32_e32 v23, v2
	v_mov_b32_e32 v24, v2
	v_mov_b32_e32 v25, v2
	v_mov_b32_e32 v30, v2
	v_mov_b32_e32 v31, v2
	v_mov_b32_e32 v32, v2
	v_mov_b32_e32 v33, v2
	v_mov_b32_e32 v38, v2
	v_mov_b32_e32 v39, v2
	v_mov_b32_e32 v40, v2
	v_mov_b32_e32 v41, v2
	v_mov_b32_e32 v46, v2
	v_mov_b32_e32 v47, v2
	v_mov_b32_e32 v48, v2
	v_mov_b32_e32 v49, v2
	v_mov_b32_e32 v54, v2
	v_mov_b32_e32 v55, v2
	v_mov_b32_e32 v56, v2
	v_mov_b32_e32 v57, v2
	v_mov_b32_e32 v58, v2
	v_mov_b32_e32 v59, v2
	v_mov_b32_e32 v60, v2
	v_mov_b32_e32 v61, v2
	v_mov_b32_e32 v62, v2
	v_mov_b32_e32 v63, v2
	v_mov_b32_e32 v64, v2
	v_mov_b32_e32 v65, v2
	v_mov_b32_e32 v66, v2
	v_mov_b32_e32 v67, v2
	v_mov_b32_e32 v68, v2
	v_mov_b32_e32 v69, v2
	v_mov_b32_e32 v70, v2
	v_mov_b32_e32 v71, v2
	v_mov_b32_e32 v72, v2
	v_mov_b32_e32 v73, v2
	v_mov_b32_e32 v74, v2
	v_mov_b32_e32 v75, v2
	v_mov_b32_e32 v76, v2
	v_mov_b32_e32 v77, v2
	v_mov_b32_e32 v82, v2
	v_mov_b32_e32 v83, v2
	v_mov_b32_e32 v84, v2
	v_mov_b32_e32 v85, v2
	v_mov_b32_e32 v90, v2
	v_mov_b32_e32 v91, v2
	v_mov_b32_e32 v92, v2
	v_mov_b32_e32 v93, v2
	v_mov_b32_e32 v98, v2
	v_mov_b32_e32 v99, v2
	v_mov_b32_e32 v100, v2
	v_mov_b32_e32 v101, v2
	v_mov_b32_e32 v106, v2
	v_mov_b32_e32 v107, v2
	v_mov_b32_e32 v108, v2
	v_mov_b32_e32 v109, v2
	v_mov_b32_e32 v114, v2
	v_mov_b32_e32 v115, v2
	v_mov_b32_e32 v116, v2
	v_mov_b32_e32 v117, v2
	v_mov_b32_e32 v78, v2
	v_mov_b32_e32 v79, v2
	v_mov_b32_e32 v80, v2
	v_mov_b32_e32 v81, v2
	v_mov_b32_e32 v86, v2
	v_mov_b32_e32 v87, v2
	v_mov_b32_e32 v88, v2
	v_mov_b32_e32 v89, v2
	v_mov_b32_e32 v94, v2
	v_mov_b32_e32 v95, v2
	v_mov_b32_e32 v96, v2
	v_mov_b32_e32 v97, v2
	v_mov_b32_e32 v102, v2
	v_mov_b32_e32 v103, v2
	v_mov_b32_e32 v104, v2
	v_mov_b32_e32 v105, v2
	v_mov_b32_e32 v110, v2
	v_mov_b32_e32 v111, v2
	v_mov_b32_e32 v112, v2
	v_mov_b32_e32 v113, v2
	v_mov_b32_e32 v118, v2
	v_mov_b32_e32 v119, v2
	v_mov_b32_e32 v120, v2
	v_mov_b32_e32 v121, v2
	v_mov_b32_e32 v122, v2
	v_mov_b32_e32 v123, v2
	v_mov_b32_e32 v124, v2
	v_mov_b32_e32 v125, v2
	v_mov_b32_e32 v126, v2
	v_mov_b32_e32 v127, v2
	v_mov_b32_e32 v128, v2
	v_mov_b32_e32 v129, v2
	.p2align	6

; template <class Epi, class Sched, bool ALIGN_EPI = false>
; __device__ __forceinline__ void gemm_phase(PG8_LAS unsigned char* lds, const Gemm g, const Sched& S, const Epi& E) {
;     ...
;     f32x4 acc[2][2][4][2];
; #pragma unroll
;     for (int a = 0; a < 2; ++a)
; #pragma unroll
;         for (int b = 0; b < 2; ++b)
; #pragma unroll
;             for (int m = 0; m < 4; ++m)
; #pragma unroll
;                 for (int n = 0; n < 2; ++n) acc[a][b][m][n] = (f32x4){0.f, 0.f, 0.f, 0.f};
;     ...
;         const char* nA = has_next ? (const char*)g.A + (size_t)nxt.pm * tstepA : cA; const char* nB = has_next ? (const char*)g.Bt + (size_t)nxt.pn * tstepB : cB;
;     ...
; #pragma unroll
;         for (int a = 0; a < 2; ++a)
; #pragma unroll
;             for (int b = 0; b < 2; ++b)
; #pragma unroll
;                 for (int m = 0; m < 4; ++m)
; #pragma unroll
;                     for (int n = 0; n < 2; ++n) acc[a][b][m][n] = (f32x4){0.f, 0.f, 0.f, 0.f};
;         cur = nxt; cA = nA; cB = nB; ++ui;
.LBB0_1163:
	s_ashr_i32 s29, s28, 31
	s_lshl_b64 s[36:37], s[28:29], 19
	s_add_u32 s36, s0, s36
	v_mov_b32_e32 v125, 0
	s_addc_u32 s37, s1, s37
	s_and_b64 vcc, exec, s[2:3]
	v_mov_b32_e32 v124, v125
	v_mov_b32_e32 v123, v125
	v_mov_b32_e32 v122, v125
	v_mov_b32_e32 v129, v125
	v_mov_b32_e32 v128, v125
	v_mov_b32_e32 v127, v125
	v_mov_b32_e32 v126, v125
	v_mov_b32_e32 v121, v125
	v_mov_b32_e32 v120, v125
	v_mov_b32_e32 v119, v125
	v_mov_b32_e32 v118, v125
	v_mov_b32_e32 v117, v125
	v_mov_b32_e32 v116, v125
	v_mov_b32_e32 v115, v125
	v_mov_b32_e32 v114, v125
	v_mov_b32_e32 v113, v125
	v_mov_b32_e32 v112, v125
	v_mov_b32_e32 v111, v125
	v_mov_b32_e32 v110, v125
	v_mov_b32_e32 v109, v125
	v_mov_b32_e32 v108, v125
	v_mov_b32_e32 v107, v125
	v_mov_b32_e32 v106, v125
	v_mov_b32_e32 v105, v125
	v_mov_b32_e32 v104, v125
	v_mov_b32_e32 v103, v125
	v_mov_b32_e32 v102, v125
	v_mov_b32_e32 v101, v125
	v_mov_b32_e32 v100, v125
	v_mov_b32_e32 v99, v125
	v_mov_b32_e32 v98, v125
	v_mov_b32_e32 v65, v125
	v_mov_b32_e32 v64, v125
	v_mov_b32_e32 v63, v125
	v_mov_b32_e32 v62, v125
	s_waitcnt vmcnt(0)
	v_mov_b32_e32 v61, v125
	v_mov_b32_e32 v60, v125
	v_mov_b32_e32 v59, v125
	v_mov_b32_e32 v58, v125
	v_mov_b32_e32 v57, v125
	v_mov_b32_e32 v56, v125
	v_mov_b32_e32 v55, v125
	v_mov_b32_e32 v54, v125
	v_mov_b32_e32 v53, v125
	v_mov_b32_e32 v52, v125
	v_mov_b32_e32 v51, v125
	v_mov_b32_e32 v50, v125
	v_mov_b32_e32 v49, v125
	v_mov_b32_e32 v48, v125
	v_mov_b32_e32 v47, v125
	v_mov_b32_e32 v46, v125
	v_mov_b32_e32 v45, v125
	v_mov_b32_e32 v44, v125
	v_mov_b32_e32 v43, v125
	v_mov_b32_e32 v42, v125
	v_mov_b32_e32 v41, v125
	v_mov_b32_e32 v40, v125
	v_mov_b32_e32 v39, v125
	v_mov_b32_e32 v38, v125
	v_mov_b32_e32 v37, v125
	v_mov_b32_e32 v36, v125
	v_mov_b32_e32 v35, v125
	v_mov_b32_e32 v34, v125
	v_mov_b32_e32 v97, v125
	v_mov_b32_e32 v96, v125
	v_mov_b32_e32 v95, v125
	v_mov_b32_e32 v94, v125
	v_mov_b32_e32 v93, v125
	v_mov_b32_e32 v92, v125
	v_mov_b32_e32 v91, v125
	v_mov_b32_e32 v90, v125
	v_mov_b32_e32 v89, v125
	v_mov_b32_e32 v88, v125
	v_mov_b32_e32 v87, v125
	v_mov_b32_e32 v86, v125
	v_mov_b32_e32 v85, v125
	v_mov_b32_e32 v84, v125
	v_mov_b32_e32 v83, v125
	v_mov_b32_e32 v82, v125
	v_mov_b32_e32 v81, v125
	v_mov_b32_e32 v80, v125
	v_mov_b32_e32 v79, v125
	v_mov_b32_e32 v78, v125
	v_mov_b32_e32 v77, v125
	v_mov_b32_e32 v76, v125
	v_mov_b32_e32 v75, v125
	v_mov_b32_e32 v74, v125
	v_mov_b32_e32 v73, v125
	v_mov_b32_e32 v72, v125
	v_mov_b32_e32 v71, v125
	v_mov_b32_e32 v70, v125
	v_mov_b32_e32 v69, v125
	v_mov_b32_e32 v68, v125
	v_mov_b32_e32 v67, v125
	v_mov_b32_e32 v66, v125
	v_mov_b32_e32 v33, v125
	v_mov_b32_e32 v32, v125
	v_mov_b32_e32 v31, v125
	v_mov_b32_e32 v30, v125
	v_mov_b32_e32 v29, v125
	v_mov_b32_e32 v28, v125
	v_mov_b32_e32 v27, v125
	v_mov_b32_e32 v26, v125
	v_mov_b32_e32 v25, v125
	v_mov_b32_e32 v24, v125
	v_mov_b32_e32 v23, v125
	v_mov_b32_e32 v22, v125
	v_mov_b32_e32 v21, v125
	v_mov_b32_e32 v20, v125
	v_mov_b32_e32 v19, v125
	v_mov_b32_e32 v18, v125
	v_mov_b32_e32 v17, v125
	v_mov_b32_e32 v16, v125
	v_mov_b32_e32 v15, v125
	v_mov_b32_e32 v14, v125
	v_mov_b32_e32 v13, v125
	v_mov_b32_e32 v12, v125
	v_mov_b32_e32 v11, v125
	v_mov_b32_e32 v10, v125
	v_mov_b32_e32 v9, v125
	v_mov_b32_e32 v8, v125
	v_mov_b32_e32 v7, v125
	v_mov_b32_e32 v6, v125
	v_mov_b32_e32 v5, v125
	v_mov_b32_e32 v4, v125
	v_mov_b32_e32 v3, v125
	v_mov_b32_e32 v2, v125
	s_cbranch_vccnz .LBB0_1166
	s_and_b64 s[6:7], s[6:7], exec
	s_cselect_b32 s29, s37, s43
	s_cselect_b32 s69, s36, s42
	s_add_u32 s6, s42, 0x40080
	s_addc_u32 s7, s43, 0
	s_add_u32 s42, s40, 0x100
	v_mov_b32_e32 v2, 0
	s_addc_u32 s43, s41, 0
	s_mov_b32 s40, 0
	v_mov_b32_e32 v3, v2
	v_mov_b32_e32 v4, v2
	v_mov_b32_e32 v5, v2
	v_mov_b32_e32 v6, v2
	v_mov_b32_e32 v7, v2
	v_mov_b32_e32 v8, v2
	v_mov_b32_e32 v9, v2
	v_mov_b32_e32 v10, v2
	v_mov_b32_e32 v11, v2
	v_mov_b32_e32 v12, v2
	v_mov_b32_e32 v13, v2
	v_mov_b32_e32 v14, v2
	v_mov_b32_e32 v15, v2
	v_mov_b32_e32 v16, v2
	v_mov_b32_e32 v17, v2
	v_mov_b32_e32 v18, v2
	v_mov_b32_e32 v19, v2
	v_mov_b32_e32 v20, v2
	v_mov_b32_e32 v21, v2
	v_mov_b32_e32 v22, v2
	v_mov_b32_e32 v23, v2
	v_mov_b32_e32 v24, v2
	v_mov_b32_e32 v25, v2
	v_mov_b32_e32 v26, v2
	v_mov_b32_e32 v27, v2
	v_mov_b32_e32 v28, v2
	v_mov_b32_e32 v29, v2
	v_mov_b32_e32 v30, v2
	v_mov_b32_e32 v31, v2
	v_mov_b32_e32 v32, v2
	v_mov_b32_e32 v33, v2
	v_mov_b32_e32 v66, v2
	v_mov_b32_e32 v67, v2
	v_mov_b32_e32 v68, v2
	v_mov_b32_e32 v69, v2
	v_mov_b32_e32 v70, v2
	v_mov_b32_e32 v71, v2
	v_mov_b32_e32 v72, v2
	v_mov_b32_e32 v73, v2
	v_mov_b32_e32 v74, v2
	v_mov_b32_e32 v75, v2
	v_mov_b32_e32 v76, v2
	v_mov_b32_e32 v77, v2
	v_mov_b32_e32 v78, v2
	v_mov_b32_e32 v79, v2
	v_mov_b32_e32 v80, v2
	v_mov_b32_e32 v81, v2
	v_mov_b32_e32 v82, v2
	v_mov_b32_e32 v83, v2
	v_mov_b32_e32 v84, v2
	v_mov_b32_e32 v85, v2
	v_mov_b32_e32 v86, v2
	v_mov_b32_e32 v87, v2
	v_mov_b32_e32 v88, v2
	v_mov_b32_e32 v89, v2
	v_mov_b32_e32 v90, v2
	v_mov_b32_e32 v91, v2
	v_mov_b32_e32 v92, v2
	v_mov_b32_e32 v93, v2
	v_mov_b32_e32 v94, v2
	v_mov_b32_e32 v95, v2
	v_mov_b32_e32 v96, v2
	v_mov_b32_e32 v97, v2
	v_mov_b32_e32 v34, v2
	v_mov_b32_e32 v35, v2
	v_mov_b32_e32 v36, v2
	v_mov_b32_e32 v37, v2
	v_mov_b32_e32 v38, v2
	v_mov_b32_e32 v39, v2
	v_mov_b32_e32 v40, v2
	v_mov_b32_e32 v41, v2
	v_mov_b32_e32 v42, v2
	v_mov_b32_e32 v43, v2
	v_mov_b32_e32 v44, v2
	v_mov_b32_e32 v45, v2
	v_mov_b32_e32 v46, v2
	v_mov_b32_e32 v47, v2
	v_mov_b32_e32 v48, v2
	v_mov_b32_e32 v49, v2
	v_mov_b32_e32 v50, v2
	v_mov_b32_e32 v51, v2
	v_mov_b32_e32 v52, v2
	v_mov_b32_e32 v53, v2
	v_mov_b32_e32 v54, v2
	v_mov_b32_e32 v55, v2
	v_mov_b32_e32 v56, v2
	v_mov_b32_e32 v57, v2
	v_mov_b32_e32 v58, v2
	v_mov_b32_e32 v59, v2
	v_mov_b32_e32 v60, v2
	v_mov_b32_e32 v61, v2
	v_mov_b32_e32 v62, v2
	v_mov_b32_e32 v63, v2
	v_mov_b32_e32 v64, v2
	v_mov_b32_e32 v65, v2
	v_mov_b32_e32 v98, v2
	v_mov_b32_e32 v99, v2
	v_mov_b32_e32 v100, v2
	v_mov_b32_e32 v101, v2
	v_mov_b32_e32 v102, v2
	v_mov_b32_e32 v103, v2
	v_mov_b32_e32 v104, v2
	v_mov_b32_e32 v105, v2
	v_mov_b32_e32 v106, v2
	v_mov_b32_e32 v107, v2
	v_mov_b32_e32 v108, v2
	v_mov_b32_e32 v109, v2
	v_mov_b32_e32 v110, v2
	v_mov_b32_e32 v111, v2
	v_mov_b32_e32 v112, v2
	v_mov_b32_e32 v113, v2
	v_mov_b32_e32 v114, v2
	v_mov_b32_e32 v115, v2
	v_mov_b32_e32 v116, v2
	v_mov_b32_e32 v117, v2
	v_mov_b32_e32 v118, v2
	v_mov_b32_e32 v119, v2
	v_mov_b32_e32 v120, v2
	v_mov_b32_e32 v121, v2
	v_mov_b32_e32 v126, v2
	v_mov_b32_e32 v127, v2
	v_mov_b32_e32 v128, v2
	v_mov_b32_e32 v129, v2
	v_mov_b32_e32 v122, v2
	v_mov_b32_e32 v123, v2
	v_mov_b32_e32 v124, v2
	v_mov_b32_e32 v125, v2
	.p2align	6

; template <class Epi, class Sched, bool ALIGN_EPI = false>
; __device__ __forceinline__ void gemm_phase(PG8_LAS unsigned char* lds, const Gemm g, const Sched& S, const Epi& E) {
;     ...
;     f32x4 acc[2][2][4][2];
; #pragma unroll
;     for (int a = 0; a < 2; ++a)
; #pragma unroll
;         for (int b = 0; b < 2; ++b)
; #pragma unroll
;             for (int m = 0; m < 4; ++m)
; #pragma unroll
;                 for (int n = 0; n < 2; ++n) acc[a][b][m][n] = (f32x4){0.f, 0.f, 0.f, 0.f};
;     ...
;         const char* nA = has_next ? (const char*)g.A + (size_t)nxt.pm * tstepA : cA; const char* nB = has_next ? (const char*)g.Bt + (size_t)nxt.pn * tstepB : cB;
;     ...
; #pragma unroll
;         for (int a = 0; a < 2; ++a)
; #pragma unroll
;             for (int b = 0; b < 2; ++b)
; #pragma unroll
;                 for (int m = 0; m < 4; ++m)
; #pragma unroll
;                     for (int n = 0; n < 2; ++n) acc[a][b][m][n] = (f32x4){0.f, 0.f, 0.f, 0.f};
;         cur = nxt; cA = nA; cB = nB; ++ui;
.LBB0_1182:
	s_ashr_i32 s41, s40, 31
	s_lshl_b64 s[44:45], s[40:41], 19
	s_add_u32 s44, s55, s44
	v_mov_b32_e32 v145, 0
	s_addc_u32 s45, s60, s45
	s_andn2_b64 vcc, exec, s[30:31]
	v_mov_b32_e32 v144, v145
	v_mov_b32_e32 v143, v145
	v_mov_b32_e32 v142, v145
	v_mov_b32_e32 v141, v145
	v_mov_b32_e32 v140, v145
	v_mov_b32_e32 v139, v145
	v_mov_b32_e32 v138, v145
	v_mov_b32_e32 v121, v145
	v_mov_b32_e32 v120, v145
	v_mov_b32_e32 v119, v145
	v_mov_b32_e32 v118, v145
	v_mov_b32_e32 v117, v145
	v_mov_b32_e32 v116, v145
	v_mov_b32_e32 v115, v145
	v_mov_b32_e32 v114, v145
	v_mov_b32_e32 v113, v145
	v_mov_b32_e32 v112, v145
	v_mov_b32_e32 v111, v145
	v_mov_b32_e32 v110, v145
	v_mov_b32_e32 v109, v145
	v_mov_b32_e32 v108, v145
	v_mov_b32_e32 v107, v145
	v_mov_b32_e32 v106, v145
	v_mov_b32_e32 v105, v145
	v_mov_b32_e32 v104, v145
	v_mov_b32_e32 v103, v145
	v_mov_b32_e32 v102, v145
	v_mov_b32_e32 v101, v145
	v_mov_b32_e32 v100, v145
	v_mov_b32_e32 v99, v145
	v_mov_b32_e32 v98, v145
	v_mov_b32_e32 v65, v145
	v_mov_b32_e32 v64, v145
	v_mov_b32_e32 v63, v145
	v_mov_b32_e32 v62, v145
	s_waitcnt vmcnt(0)
	v_mov_b32_e32 v61, v145
	v_mov_b32_e32 v60, v145
	v_mov_b32_e32 v59, v145
	v_mov_b32_e32 v58, v145
	v_mov_b32_e32 v57, v145
	v_mov_b32_e32 v56, v145
	v_mov_b32_e32 v55, v145
	v_mov_b32_e32 v54, v145
	v_mov_b32_e32 v53, v145
	v_mov_b32_e32 v52, v145
	v_mov_b32_e32 v51, v145
	v_mov_b32_e32 v50, v145
	v_mov_b32_e32 v49, v145
	v_mov_b32_e32 v48, v145
	v_mov_b32_e32 v47, v145
	v_mov_b32_e32 v46, v145
	v_mov_b32_e32 v45, v145
	v_mov_b32_e32 v44, v145
	v_mov_b32_e32 v43, v145
	v_mov_b32_e32 v42, v145
	v_mov_b32_e32 v41, v145
	v_mov_b32_e32 v40, v145
	v_mov_b32_e32 v39, v145
	v_mov_b32_e32 v38, v145
	v_mov_b32_e32 v37, v145
	v_mov_b32_e32 v36, v145
	v_mov_b32_e32 v35, v145
	v_mov_b32_e32 v34, v145
	v_mov_b32_e32 v97, v145
	v_mov_b32_e32 v96, v145
	v_mov_b32_e32 v95, v145
	v_mov_b32_e32 v94, v145
	v_mov_b32_e32 v93, v145
	v_mov_b32_e32 v92, v145
	v_mov_b32_e32 v91, v145
	v_mov_b32_e32 v90, v145
	v_mov_b32_e32 v89, v145
	v_mov_b32_e32 v88, v145
	v_mov_b32_e32 v87, v145
	v_mov_b32_e32 v86, v145
	v_mov_b32_e32 v85, v145
	v_mov_b32_e32 v84, v145
	v_mov_b32_e32 v83, v145
	v_mov_b32_e32 v82, v145
	v_mov_b32_e32 v81, v145
	v_mov_b32_e32 v80, v145
	v_mov_b32_e32 v79, v145
	v_mov_b32_e32 v78, v145
	v_mov_b32_e32 v77, v145
	v_mov_b32_e32 v76, v145
	v_mov_b32_e32 v75, v145
	v_mov_b32_e32 v74, v145
	v_mov_b32_e32 v73, v145
	v_mov_b32_e32 v72, v145
	v_mov_b32_e32 v71, v145
	v_mov_b32_e32 v70, v145
	v_mov_b32_e32 v69, v145
	v_mov_b32_e32 v68, v145
	v_mov_b32_e32 v67, v145
	v_mov_b32_e32 v66, v145
	v_mov_b32_e32 v33, v145
	v_mov_b32_e32 v32, v145
	v_mov_b32_e32 v31, v145
	v_mov_b32_e32 v30, v145
	v_mov_b32_e32 v29, v145
	v_mov_b32_e32 v28, v145
	v_mov_b32_e32 v27, v145
	v_mov_b32_e32 v26, v145
	v_mov_b32_e32 v25, v145
	v_mov_b32_e32 v24, v145
	v_mov_b32_e32 v23, v145
	v_mov_b32_e32 v22, v145
	v_mov_b32_e32 v21, v145
	v_mov_b32_e32 v20, v145
	v_mov_b32_e32 v19, v145
	v_mov_b32_e32 v18, v145
	v_mov_b32_e32 v17, v145
	v_mov_b32_e32 v16, v145
	v_mov_b32_e32 v15, v145
	v_mov_b32_e32 v14, v145
	v_mov_b32_e32 v13, v145
	v_mov_b32_e32 v12, v145
	v_mov_b32_e32 v11, v145
	v_mov_b32_e32 v10, v145
	v_mov_b32_e32 v9, v145
	v_mov_b32_e32 v8, v145
	v_mov_b32_e32 v7, v145
	v_mov_b32_e32 v6, v145
	v_mov_b32_e32 v5, v145
	v_mov_b32_e32 v4, v145
	v_mov_b32_e32 v3, v145
	v_mov_b32_e32 v2, v145
	s_cbranch_vccnz .LBB0_1185
	s_and_b64 s[4:5], s[4:5], exec
	s_cselect_b32 s1, s45, s49
	s_cselect_b32 s7, s44, s48
	s_add_u32 s4, s48, 0x40080
	s_addc_u32 s5, s49, 0
	s_add_u32 s41, s46, 0x100
	v_mov_b32_e32 v2, 0
	s_addc_u32 s48, s47, 0
	s_mov_b32 s46, 0
	v_mov_b32_e32 v3, v2
	v_mov_b32_e32 v4, v2
	v_mov_b32_e32 v5, v2
	v_mov_b32_e32 v6, v2
	v_mov_b32_e32 v7, v2
	v_mov_b32_e32 v8, v2
	v_mov_b32_e32 v9, v2
	v_mov_b32_e32 v10, v2
	v_mov_b32_e32 v11, v2
	v_mov_b32_e32 v12, v2
	v_mov_b32_e32 v13, v2
	v_mov_b32_e32 v14, v2
	v_mov_b32_e32 v15, v2
	v_mov_b32_e32 v16, v2
	v_mov_b32_e32 v17, v2
	v_mov_b32_e32 v18, v2
	v_mov_b32_e32 v19, v2
	v_mov_b32_e32 v20, v2
	v_mov_b32_e32 v21, v2
	v_mov_b32_e32 v22, v2
	v_mov_b32_e32 v23, v2
	v_mov_b32_e32 v24, v2
	v_mov_b32_e32 v25, v2
	v_mov_b32_e32 v26, v2
	v_mov_b32_e32 v27, v2
	v_mov_b32_e32 v28, v2
	v_mov_b32_e32 v29, v2
	v_mov_b32_e32 v30, v2
	v_mov_b32_e32 v31, v2
	v_mov_b32_e32 v32, v2
	v_mov_b32_e32 v33, v2
	v_mov_b32_e32 v66, v2
	v_mov_b32_e32 v67, v2
	v_mov_b32_e32 v68, v2
	v_mov_b32_e32 v69, v2
	v_mov_b32_e32 v70, v2
	v_mov_b32_e32 v71, v2
	v_mov_b32_e32 v72, v2
	v_mov_b32_e32 v73, v2
	v_mov_b32_e32 v74, v2
	v_mov_b32_e32 v75, v2
	v_mov_b32_e32 v76, v2
	v_mov_b32_e32 v77, v2
	v_mov_b32_e32 v78, v2
	v_mov_b32_e32 v79, v2
	v_mov_b32_e32 v80, v2
	v_mov_b32_e32 v81, v2
	v_mov_b32_e32 v82, v2
	v_mov_b32_e32 v83, v2
	v_mov_b32_e32 v84, v2
	v_mov_b32_e32 v85, v2
	v_mov_b32_e32 v86, v2
	v_mov_b32_e32 v87, v2
	v_mov_b32_e32 v88, v2
	v_mov_b32_e32 v89, v2
	v_mov_b32_e32 v90, v2
	v_mov_b32_e32 v91, v2
	v_mov_b32_e32 v92, v2
	v_mov_b32_e32 v93, v2
	v_mov_b32_e32 v94, v2
	v_mov_b32_e32 v95, v2
	v_mov_b32_e32 v96, v2
	v_mov_b32_e32 v97, v2
	v_mov_b32_e32 v34, v2
	v_mov_b32_e32 v35, v2
	v_mov_b32_e32 v36, v2
	v_mov_b32_e32 v37, v2
	v_mov_b32_e32 v38, v2
	v_mov_b32_e32 v39, v2
	v_mov_b32_e32 v40, v2
	v_mov_b32_e32 v41, v2
	v_mov_b32_e32 v42, v2
	v_mov_b32_e32 v43, v2
	v_mov_b32_e32 v44, v2
	v_mov_b32_e32 v45, v2
	v_mov_b32_e32 v46, v2
	v_mov_b32_e32 v47, v2
	v_mov_b32_e32 v48, v2
	v_mov_b32_e32 v49, v2
	v_mov_b32_e32 v50, v2
	v_mov_b32_e32 v51, v2
	v_mov_b32_e32 v52, v2
	v_mov_b32_e32 v53, v2
	v_mov_b32_e32 v54, v2
	v_mov_b32_e32 v55, v2
	v_mov_b32_e32 v56, v2
	v_mov_b32_e32 v57, v2
	v_mov_b32_e32 v58, v2
	v_mov_b32_e32 v59, v2
	v_mov_b32_e32 v60, v2
	v_mov_b32_e32 v61, v2
	v_mov_b32_e32 v62, v2
	v_mov_b32_e32 v63, v2
	v_mov_b32_e32 v64, v2
	v_mov_b32_e32 v65, v2
	v_mov_b32_e32 v98, v2
	v_mov_b32_e32 v99, v2
	v_mov_b32_e32 v100, v2
	v_mov_b32_e32 v101, v2
	v_mov_b32_e32 v102, v2
	v_mov_b32_e32 v103, v2
	v_mov_b32_e32 v104, v2
	v_mov_b32_e32 v105, v2
	v_mov_b32_e32 v106, v2
	v_mov_b32_e32 v107, v2
	v_mov_b32_e32 v108, v2
	v_mov_b32_e32 v109, v2
	v_mov_b32_e32 v110, v2
	v_mov_b32_e32 v111, v2
	v_mov_b32_e32 v112, v2
	v_mov_b32_e32 v113, v2
	v_mov_b32_e32 v114, v2
	v_mov_b32_e32 v115, v2
	v_mov_b32_e32 v116, v2
	v_mov_b32_e32 v117, v2
	v_mov_b32_e32 v118, v2
	v_mov_b32_e32 v119, v2
	v_mov_b32_e32 v120, v2
	v_mov_b32_e32 v121, v2
	v_mov_b32_e32 v138, v2
	v_mov_b32_e32 v139, v2
	v_mov_b32_e32 v140, v2
	v_mov_b32_e32 v141, v2
	v_mov_b32_e32 v142, v2
	v_mov_b32_e32 v143, v2
	v_mov_b32_e32 v144, v2
	v_mov_b32_e32 v145, v2
	.p2align	6

; template <class Epi, class Sched, bool ALIGN_EPI = false>
; __device__ __forceinline__ void gemm_phase(PG8_LAS unsigned char* lds, const Gemm g, const Sched& S, const Epi& E) {
;     ...
;     f32x4 acc[2][2][4][2];
; #pragma unroll
;     for (int a = 0; a < 2; ++a)
; #pragma unroll
;         for (int b = 0; b < 2; ++b)
; #pragma unroll
;             for (int m = 0; m < 4; ++m)
; #pragma unroll
;                 for (int n = 0; n < 2; ++n) acc[a][b][m][n] = (f32x4){0.f, 0.f, 0.f, 0.f};
;     ...
;         const char* nA = has_next ? (const char*)g.A + (size_t)nxt.pm * tstepA : cA; const char* nB = has_next ? (const char*)g.Bt + (size_t)nxt.pn * tstepB : cB;
;     ...
; #pragma unroll
;         for (int a = 0; a < 2; ++a)
; #pragma unroll
;             for (int b = 0; b < 2; ++b)
; #pragma unroll
;                 for (int m = 0; m < 4; ++m)
; #pragma unroll
;                     for (int n = 0; n < 2; ++n) acc[a][b][m][n] = (f32x4){0.f, 0.f, 0.f, 0.f};
;         cur = nxt; cA = nA; cB = nB; ++ui;
.LBB0_1209:
	s_ashr_i32 s25, s24, 31
	s_lshl_b64 s[28:29], s[24:25], 19
	s_add_u32 s28, s1, s28
	v_mov_b32_e32 v129, 0
	s_addc_u32 s29, s36, s29
	s_and_b64 vcc, exec, s[2:3]
	v_mov_b32_e32 v128, v129
	v_mov_b32_e32 v127, v129
	v_mov_b32_e32 v126, v129
	v_mov_b32_e32 v125, v129
	v_mov_b32_e32 v124, v129
	v_mov_b32_e32 v123, v129
	v_mov_b32_e32 v122, v129
	v_mov_b32_e32 v121, v129
	v_mov_b32_e32 v120, v129
	v_mov_b32_e32 v119, v129
	v_mov_b32_e32 v118, v129
	v_mov_b32_e32 v117, v129
	v_mov_b32_e32 v116, v129
	v_mov_b32_e32 v115, v129
	v_mov_b32_e32 v114, v129
	v_mov_b32_e32 v113, v129
	v_mov_b32_e32 v112, v129
	v_mov_b32_e32 v111, v129
	v_mov_b32_e32 v110, v129
	v_mov_b32_e32 v109, v129
	v_mov_b32_e32 v108, v129
	v_mov_b32_e32 v107, v129
	v_mov_b32_e32 v106, v129
	v_mov_b32_e32 v105, v129
	v_mov_b32_e32 v104, v129
	v_mov_b32_e32 v103, v129
	v_mov_b32_e32 v102, v129
	v_mov_b32_e32 v101, v129
	v_mov_b32_e32 v100, v129
	v_mov_b32_e32 v99, v129
	v_mov_b32_e32 v98, v129
	v_mov_b32_e32 v65, v129
	v_mov_b32_e32 v64, v129
	v_mov_b32_e32 v63, v129
	v_mov_b32_e32 v62, v129
	v_mov_b32_e32 v61, v129
	v_mov_b32_e32 v60, v129
	v_mov_b32_e32 v59, v129
	v_mov_b32_e32 v58, v129
	v_mov_b32_e32 v57, v129
	v_mov_b32_e32 v56, v129
	v_mov_b32_e32 v55, v129
	v_mov_b32_e32 v54, v129
	v_mov_b32_e32 v53, v129
	v_mov_b32_e32 v52, v129
	v_mov_b32_e32 v51, v129
	v_mov_b32_e32 v50, v129
	v_mov_b32_e32 v49, v129
	v_mov_b32_e32 v48, v129
	v_mov_b32_e32 v47, v129
	v_mov_b32_e32 v46, v129
	v_mov_b32_e32 v45, v129
	v_mov_b32_e32 v44, v129
	v_mov_b32_e32 v43, v129
	v_mov_b32_e32 v42, v129
	v_mov_b32_e32 v41, v129
	v_mov_b32_e32 v40, v129
	v_mov_b32_e32 v39, v129
	v_mov_b32_e32 v38, v129
	v_mov_b32_e32 v37, v129
	v_mov_b32_e32 v36, v129
	v_mov_b32_e32 v35, v129
	v_mov_b32_e32 v34, v129
	v_mov_b32_e32 v97, v129
	v_mov_b32_e32 v96, v129
	v_mov_b32_e32 v95, v129
	v_mov_b32_e32 v94, v129
	v_mov_b32_e32 v93, v129
	v_mov_b32_e32 v92, v129
	v_mov_b32_e32 v91, v129
	v_mov_b32_e32 v90, v129
	v_mov_b32_e32 v89, v129
	v_mov_b32_e32 v88, v129
	v_mov_b32_e32 v87, v129
	v_mov_b32_e32 v86, v129
	v_mov_b32_e32 v85, v129
	v_mov_b32_e32 v84, v129
	v_mov_b32_e32 v83, v129
	v_mov_b32_e32 v82, v129
	v_mov_b32_e32 v81, v129
	v_mov_b32_e32 v80, v129
	v_mov_b32_e32 v79, v129
	v_mov_b32_e32 v78, v129
	v_mov_b32_e32 v77, v129
	v_mov_b32_e32 v76, v129
	v_mov_b32_e32 v75, v129
	v_mov_b32_e32 v74, v129
	v_mov_b32_e32 v73, v129
	v_mov_b32_e32 v72, v129
	v_mov_b32_e32 v71, v129
	v_mov_b32_e32 v70, v129
	v_mov_b32_e32 v69, v129
	v_mov_b32_e32 v68, v129
	v_mov_b32_e32 v67, v129
	v_mov_b32_e32 v66, v129
	v_mov_b32_e32 v33, v129
	v_mov_b32_e32 v32, v129
	v_mov_b32_e32 v31, v129
	v_mov_b32_e32 v30, v129
	v_mov_b32_e32 v29, v129
	v_mov_b32_e32 v28, v129
	v_mov_b32_e32 v27, v129
	v_mov_b32_e32 v26, v129
	v_mov_b32_e32 v25, v129
	v_mov_b32_e32 v24, v129
	v_mov_b32_e32 v23, v129
	v_mov_b32_e32 v22, v129
	v_mov_b32_e32 v21, v129
	v_mov_b32_e32 v20, v129
	v_mov_b32_e32 v19, v129
	v_mov_b32_e32 v18, v129
	v_mov_b32_e32 v17, v129
	v_mov_b32_e32 v16, v129
	v_mov_b32_e32 v15, v129
	v_mov_b32_e32 v14, v129
	v_mov_b32_e32 v13, v129
	v_mov_b32_e32 v12, v129
	v_mov_b32_e32 v11, v129
	v_mov_b32_e32 v10, v129
	v_mov_b32_e32 v9, v129
	v_mov_b32_e32 v8, v129
	v_mov_b32_e32 v7, v129
	v_mov_b32_e32 v6, v129
	v_mov_b32_e32 v5, v129
	v_mov_b32_e32 v4, v129
	v_mov_b32_e32 v3, v129
	v_mov_b32_e32 v2, v129
	s_cbranch_vccnz .LBB0_1212
	s_and_b64 s[6:7], s[6:7], exec
	s_cselect_b32 s25, s29, s35
	s_cselect_b32 s54, s28, s34
	s_add_u32 s6, s34, 0x40080
	s_addc_u32 s7, s35, 0
	s_add_u32 s34, s30, 0x100
	v_mov_b32_e32 v2, 0
	s_addc_u32 s35, s31, 0
	s_mov_b32 s30, 0
	v_mov_b32_e32 v3, v2
	v_mov_b32_e32 v4, v2
	v_mov_b32_e32 v5, v2
	v_mov_b32_e32 v6, v2
	v_mov_b32_e32 v7, v2
	v_mov_b32_e32 v8, v2
	v_mov_b32_e32 v9, v2
	v_mov_b32_e32 v10, v2
	v_mov_b32_e32 v11, v2
	v_mov_b32_e32 v12, v2
	v_mov_b32_e32 v13, v2
	v_mov_b32_e32 v14, v2
	v_mov_b32_e32 v15, v2
	v_mov_b32_e32 v16, v2
	v_mov_b32_e32 v17, v2
	v_mov_b32_e32 v18, v2
	v_mov_b32_e32 v19, v2
	v_mov_b32_e32 v20, v2
	v_mov_b32_e32 v21, v2
	v_mov_b32_e32 v22, v2
	v_mov_b32_e32 v23, v2
	v_mov_b32_e32 v24, v2
	v_mov_b32_e32 v25, v2
	v_mov_b32_e32 v26, v2
	v_mov_b32_e32 v27, v2
	v_mov_b32_e32 v28, v2
	v_mov_b32_e32 v29, v2
	v_mov_b32_e32 v30, v2
	v_mov_b32_e32 v31, v2
	v_mov_b32_e32 v32, v2
	v_mov_b32_e32 v33, v2
	v_mov_b32_e32 v66, v2
	v_mov_b32_e32 v67, v2
	v_mov_b32_e32 v68, v2
	v_mov_b32_e32 v69, v2
	v_mov_b32_e32 v70, v2
	v_mov_b32_e32 v71, v2
	v_mov_b32_e32 v72, v2
	v_mov_b32_e32 v73, v2
	v_mov_b32_e32 v74, v2
	v_mov_b32_e32 v75, v2
	v_mov_b32_e32 v76, v2
	v_mov_b32_e32 v77, v2
	v_mov_b32_e32 v78, v2
	v_mov_b32_e32 v79, v2
	v_mov_b32_e32 v80, v2
	v_mov_b32_e32 v81, v2
	v_mov_b32_e32 v82, v2
	v_mov_b32_e32 v83, v2
	v_mov_b32_e32 v84, v2
	v_mov_b32_e32 v85, v2
	v_mov_b32_e32 v86, v2
	v_mov_b32_e32 v87, v2
	v_mov_b32_e32 v88, v2
	v_mov_b32_e32 v89, v2
	v_mov_b32_e32 v90, v2
	v_mov_b32_e32 v91, v2
	v_mov_b32_e32 v92, v2
	v_mov_b32_e32 v93, v2
	v_mov_b32_e32 v94, v2
	v_mov_b32_e32 v95, v2
	v_mov_b32_e32 v96, v2
	v_mov_b32_e32 v97, v2
	v_mov_b32_e32 v34, v2
	v_mov_b32_e32 v35, v2
	v_mov_b32_e32 v36, v2
	v_mov_b32_e32 v37, v2
	v_mov_b32_e32 v38, v2
	v_mov_b32_e32 v39, v2
	v_mov_b32_e32 v40, v2
	v_mov_b32_e32 v41, v2
	v_mov_b32_e32 v42, v2
	v_mov_b32_e32 v43, v2
	v_mov_b32_e32 v44, v2
	v_mov_b32_e32 v45, v2
	v_mov_b32_e32 v46, v2
	v_mov_b32_e32 v47, v2
	v_mov_b32_e32 v48, v2
	v_mov_b32_e32 v49, v2
	v_mov_b32_e32 v50, v2
	v_mov_b32_e32 v51, v2
	v_mov_b32_e32 v52, v2
	v_mov_b32_e32 v53, v2
	v_mov_b32_e32 v54, v2
	v_mov_b32_e32 v55, v2
	v_mov_b32_e32 v56, v2
	v_mov_b32_e32 v57, v2
	v_mov_b32_e32 v58, v2
	v_mov_b32_e32 v59, v2
	v_mov_b32_e32 v60, v2
	v_mov_b32_e32 v61, v2
	v_mov_b32_e32 v62, v2
	v_mov_b32_e32 v63, v2
	v_mov_b32_e32 v64, v2
	v_mov_b32_e32 v65, v2
	v_mov_b32_e32 v98, v2
	v_mov_b32_e32 v99, v2
	v_mov_b32_e32 v100, v2
	v_mov_b32_e32 v101, v2
	v_mov_b32_e32 v102, v2
	v_mov_b32_e32 v103, v2
	v_mov_b32_e32 v104, v2
	v_mov_b32_e32 v105, v2
	v_mov_b32_e32 v106, v2
	v_mov_b32_e32 v107, v2
	v_mov_b32_e32 v108, v2
	v_mov_b32_e32 v109, v2
	v_mov_b32_e32 v110, v2
	v_mov_b32_e32 v111, v2
	v_mov_b32_e32 v112, v2
	v_mov_b32_e32 v113, v2
	v_mov_b32_e32 v114, v2
	v_mov_b32_e32 v115, v2
	v_mov_b32_e32 v116, v2
	v_mov_b32_e32 v117, v2
	v_mov_b32_e32 v118, v2
	v_mov_b32_e32 v119, v2
	v_mov_b32_e32 v120, v2
	v_mov_b32_e32 v121, v2
	v_mov_b32_e32 v122, v2
	v_mov_b32_e32 v123, v2
	v_mov_b32_e32 v124, v2
	v_mov_b32_e32 v125, v2
	v_mov_b32_e32 v126, v2
	v_mov_b32_e32 v127, v2
	v_mov_b32_e32 v128, v2
	v_mov_b32_e32 v129, v2
	.p2align	6

; template <class Epi, class Sched, bool ALIGN_EPI = false>
; __device__ __forceinline__ void gemm_phase(PG8_LAS unsigned char* lds, const Gemm g, const Sched& S, const Epi& E) {
;     ...
;         const bool has_next = S.next(ui + 1, nxt);
;         const char* nA = has_next ? (const char*)g.A + (size_t)nxt.pm * tstepA : cA; const char* nB = has_next ? (const char*)g.Bt + (size_t)nxt.pn * tstepB : cB;
;         for (int t = 0; t < nt; t += 2) {
;             const bool last = (t == nt - 2);
;             const char* a1 = cA + (size_t)(t + 1) * kstep;
;             const char* a2 = last ? nA : cA + (size_t)(t + 2) * kstep; const char* b2 = last ? nB : cB + (size_t)(t + 2) * kstep;
;             const char* a3 = a2 + kstep; const char* b3 = b2 + kstep;
;     ...
; #pragma unroll
;         for (int a = 0; a < 2; ++a)
; #pragma unroll
;             for (int b = 0; b < 2; ++b)
; #pragma unroll
;                 for (int m = 0; m < 4; ++m)
; #pragma unroll
;                     for (int n = 0; n < 2; ++n) acc[a][b][m][n] = (f32x4){0.f, 0.f, 0.f, 0.f};
;         cur = nxt; cA = nA; cB = nB; ++ui;
.LBB0_1422:
	s_ashr_i32 s25, s24, 31
	s_lshl_b64 s[26:27], s[24:25], 21
	s_add_u32 s26, s1, s26
	s_addc_u32 s27, s40, s27
	s_and_b64 s[28:29], s[2:3], exec
	s_cselect_b32 s25, s27, s35
	s_cselect_b32 s62, s26, s34
	s_ashr_i32 s23, s22, 31
	s_lshl_b64 s[28:29], s[22:23], 21
	s_add_u32 s28, s41, s28
	s_addc_u32 s29, s42, s29
	s_and_b64 s[38:39], s[2:3], exec
	s_cselect_b32 s23, s29, s37
	s_cselect_b32 s63, s28, s36
	s_add_u32 s34, s34, 0x100080
	s_addc_u32 s35, s35, 0
	s_add_u32 s64, s36, 0x100
	v_mov_b32_e32 v2, 0
	s_addc_u32 s65, s37, 0
	s_mov_b32 s66, -2
	v_mov_b32_e32 v3, v2
	v_mov_b32_e32 v4, v2
	v_mov_b32_e32 v5, v2
	v_mov_b32_e32 v6, v2
	v_mov_b32_e32 v7, v2
	v_mov_b32_e32 v8, v2
	v_mov_b32_e32 v9, v2
	v_mov_b32_e32 v14, v2
	v_mov_b32_e32 v15, v2
	v_mov_b32_e32 v16, v2
	v_mov_b32_e32 v17, v2
	v_mov_b32_e32 v22, v2
	v_mov_b32_e32 v23, v2
	v_mov_b32_e32 v24, v2
	v_mov_b32_e32 v25, v2
	v_mov_b32_e32 v30, v2
	v_mov_b32_e32 v31, v2
	v_mov_b32_e32 v32, v2
	v_mov_b32_e32 v33, v2
	v_mov_b32_e32 v38, v2
	v_mov_b32_e32 v39, v2
	v_mov_b32_e32 v40, v2
	v_mov_b32_e32 v41, v2
	s_waitcnt vmcnt(0)
	v_mov_b32_e32 v46, v2
	v_mov_b32_e32 v47, v2
	v_mov_b32_e32 v48, v2
	v_mov_b32_e32 v49, v2
	v_mov_b32_e32 v54, v2
	v_mov_b32_e32 v55, v2
	v_mov_b32_e32 v56, v2
	v_mov_b32_e32 v57, v2
	v_mov_b32_e32 v10, v2
	v_mov_b32_e32 v11, v2
	v_mov_b32_e32 v12, v2
	v_mov_b32_e32 v13, v2
	v_mov_b32_e32 v18, v2
	v_mov_b32_e32 v19, v2
	v_mov_b32_e32 v20, v2
	v_mov_b32_e32 v21, v2
	v_mov_b32_e32 v26, v2
	v_mov_b32_e32 v27, v2
	v_mov_b32_e32 v28, v2
	v_mov_b32_e32 v29, v2
	v_mov_b32_e32 v34, v2
	v_mov_b32_e32 v35, v2
	v_mov_b32_e32 v36, v2
	v_mov_b32_e32 v37, v2
	v_mov_b32_e32 v42, v2
	v_mov_b32_e32 v43, v2
	v_mov_b32_e32 v44, v2
	v_mov_b32_e32 v45, v2
	v_mov_b32_e32 v50, v2
	v_mov_b32_e32 v51, v2
	v_mov_b32_e32 v52, v2
	v_mov_b32_e32 v53, v2
	v_mov_b32_e32 v58, v2
	v_mov_b32_e32 v59, v2
	v_mov_b32_e32 v60, v2
	v_mov_b32_e32 v61, v2
	v_mov_b32_e32 v62, v2
	v_mov_b32_e32 v63, v2
	v_mov_b32_e32 v64, v2
	v_mov_b32_e32 v65, v2
	v_mov_b32_e32 v66, v2
	v_mov_b32_e32 v67, v2
	v_mov_b32_e32 v68, v2
	v_mov_b32_e32 v69, v2
	v_mov_b32_e32 v70, v2
	v_mov_b32_e32 v71, v2
	v_mov_b32_e32 v72, v2
	v_mov_b32_e32 v73, v2
	v_mov_b32_e32 v78, v2
	v_mov_b32_e32 v79, v2
	v_mov_b32_e32 v80, v2
	v_mov_b32_e32 v81, v2
	v_mov_b32_e32 v86, v2
	v_mov_b32_e32 v87, v2
	v_mov_b32_e32 v88, v2
	v_mov_b32_e32 v89, v2
	v_mov_b32_e32 v94, v2
	v_mov_b32_e32 v95, v2
	v_mov_b32_e32 v96, v2
	v_mov_b32_e32 v97, v2
	v_mov_b32_e32 v102, v2
	v_mov_b32_e32 v103, v2
	v_mov_b32_e32 v104, v2
	v_mov_b32_e32 v105, v2
	v_mov_b32_e32 v110, v2
	v_mov_b32_e32 v111, v2
	v_mov_b32_e32 v112, v2
	v_mov_b32_e32 v113, v2
	v_mov_b32_e32 v118, v2
	v_mov_b32_e32 v119, v2
	v_mov_b32_e32 v120, v2
	v_mov_b32_e32 v121, v2
	v_mov_b32_e32 v74, v2
	v_mov_b32_e32 v75, v2
	v_mov_b32_e32 v76, v2
	v_mov_b32_e32 v77, v2
	v_mov_b32_e32 v82, v2
	v_mov_b32_e32 v83, v2
	v_mov_b32_e32 v84, v2
	v_mov_b32_e32 v85, v2
	v_mov_b32_e32 v90, v2
	v_mov_b32_e32 v91, v2
	v_mov_b32_e32 v92, v2
	v_mov_b32_e32 v93, v2
	v_mov_b32_e32 v98, v2
	v_mov_b32_e32 v99, v2
	v_mov_b32_e32 v100, v2
	v_mov_b32_e32 v101, v2
	v_mov_b32_e32 v106, v2
	v_mov_b32_e32 v107, v2
	v_mov_b32_e32 v108, v2
	v_mov_b32_e32 v109, v2
	v_mov_b32_e32 v114, v2
	v_mov_b32_e32 v115, v2
	v_mov_b32_e32 v116, v2
	v_mov_b32_e32 v117, v2
	v_mov_b32_e32 v122, v2
	v_mov_b32_e32 v123, v2
	v_mov_b32_e32 v124, v2
	v_mov_b32_e32 v125, v2
	v_mov_b32_e32 v126, v2
	v_mov_b32_e32 v127, v2
	v_mov_b32_e32 v128, v2
	v_mov_b32_e32 v129, v2
	.p2align	6

; template <class Epi, class Sched, bool ALIGN_EPI = false>
; __device__ __forceinline__ void gemm_phase(PG8_LAS unsigned char* lds, const Gemm g, const Sched& S, const Epi& E) {
;     ...
;         const bool has_next = S.next(ui + 1, nxt);
;         const char* nA = has_next ? (const char*)g.A + (size_t)nxt.pm * tstepA : cA; const char* nB = has_next ? (const char*)g.Bt + (size_t)nxt.pn * tstepB : cB;
;         for (int t = 0; t < nt; t += 2) {
;             const bool last = (t == nt - 2);
;             const char* a1 = cA + (size_t)(t + 1) * kstep;
;             const char* a2 = last ? nA : cA + (size_t)(t + 2) * kstep; const char* b2 = last ? nB : cB + (size_t)(t + 2) * kstep;
;             const char* a3 = a2 + kstep; const char* b3 = b2 + kstep;
;     ...
; #pragma unroll
;         for (int a = 0; a < 2; ++a)
; #pragma unroll
;             for (int b = 0; b < 2; ++b)
; #pragma unroll
;                 for (int m = 0; m < 4; ++m)
; #pragma unroll
;                     for (int n = 0; n < 2; ++n) acc[a][b][m][n] = (f32x4){0.f, 0.f, 0.f, 0.f};
;         cur = nxt; cA = nA; cB = nB; ++ui;
;     __device__ __forceinline__ void operator()(const f32x4 (&acc)[2][2][4][2], const Unit& u, int, int, int, int) const {
;     ...
;                 const f32x4 w0 = *(const f32x4*)(cw + c0 + 4 * n), w1 = *(const f32x4*)(cw + DFF + c0 + 4 * n), w2 = *(const f32x4*)(cw + 2 * DFF + c0 + 4 * n), bb = *(const f32x4*)(cb + c0 + 4 * n);
.LBB0_1543:
	s_ashr_i32 s43, s42, 31
	s_lshl_b64 s[4:5], s[42:43], 21
	s_add_u32 s44, s0, s4
	s_addc_u32 s45, s1, s5
	s_and_b64 s[4:5], s[2:3], exec
	s_cselect_b32 s43, s45, s51
	s_cselect_b32 s74, s44, s50
	s_ashr_i32 s41, s40, 31
	s_lshl_b64 s[4:5], s[40:41], 21
	s_add_u32 s46, s52, s4
	s_addc_u32 s47, s53, s5
	s_and_b64 s[4:5], s[2:3], exec
	s_cselect_b32 s41, s47, s49
	s_cselect_b32 s75, s46, s48
	s_add_u32 s4, s50, 0x100080
	s_addc_u32 s5, s51, 0
	s_add_u32 s50, s48, 0x100
	v_mov_b32_e32 v18, 0
	s_addc_u32 s51, s49, 0
	s_mov_b32 s76, -2
	v_mov_b32_e32 v19, v18
	v_mov_b32_e32 v20, v18
	v_mov_b32_e32 v21, v18
	s_lshl_b32 s98, s9, 7
	v_readfirstlane_b32 s99, v0
	s_nop 3
	s_lshr_b32 s99, s99, 1
	s_and_b32 s99, s99, 0x60
	s_or_b32 s98, s99, s98
	v_lshrrev_b32_e32 v250, 1, v0
	v_and_or_b32 v250, v250, 24, s98
	v_lshlrev_b32_e32 v250, 2, v250
	global_load_dwordx4 v[216:219], v250, s[22:23]
	global_load_dwordx4 v[220:223], v250, s[24:25]
	global_load_dwordx4 v[224:227], v250, s[26:27]
	global_load_dwordx4 v[230:233], v250, s[28:29]
	global_load_dwordx4 v[234:237], v250, s[22:23] offset:16
	global_load_dwordx4 v[238:241], v250, s[24:25] offset:16
	global_load_dwordx4 v[242:245], v250, s[26:27] offset:16
	global_load_dwordx4 v[246:249], v250, s[28:29] offset:16
	s_waitcnt vmcnt(0)
	v_mov_b32_e32 v46, v18
	v_mov_b32_e32 v47, v18
	v_mov_b32_e32 v48, v18
	v_mov_b32_e32 v49, v18
	v_mov_b32_e32 v30, v18
	v_mov_b32_e32 v31, v18
	v_mov_b32_e32 v32, v18
	v_mov_b32_e32 v33, v18
	v_mov_b32_e32 v50, v18
	v_mov_b32_e32 v51, v18
	v_mov_b32_e32 v52, v18
	v_mov_b32_e32 v53, v18
	v_mov_b32_e32 v34, v18
	v_mov_b32_e32 v35, v18
	v_mov_b32_e32 v36, v18
	v_mov_b32_e32 v37, v18
	v_mov_b32_e32 v54, v18
	v_mov_b32_e32 v55, v18
	v_mov_b32_e32 v56, v18
	v_mov_b32_e32 v57, v18
	v_mov_b32_e32 v10, v18
	v_mov_b32_e32 v11, v18
	v_mov_b32_e32 v12, v18
	v_mov_b32_e32 v13, v18
	v_mov_b32_e32 v14, v18
	v_mov_b32_e32 v15, v18
	v_mov_b32_e32 v16, v18
	v_mov_b32_e32 v17, v18
	v_mov_b32_e32 v2, v18
	v_mov_b32_e32 v3, v18
	v_mov_b32_e32 v4, v18
	v_mov_b32_e32 v5, v18
	v_mov_b32_e32 v6, v18
	v_mov_b32_e32 v7, v18
	v_mov_b32_e32 v8, v18
	v_mov_b32_e32 v9, v18
	v_mov_b32_e32 v38, v18
	v_mov_b32_e32 v39, v18
	v_mov_b32_e32 v40, v18
	v_mov_b32_e32 v41, v18
	v_mov_b32_e32 v58, v18
	v_mov_b32_e32 v59, v18
	v_mov_b32_e32 v60, v18
	v_mov_b32_e32 v61, v18
	v_mov_b32_e32 v42, v18
	v_mov_b32_e32 v43, v18
	v_mov_b32_e32 v44, v18
	v_mov_b32_e32 v45, v18
	v_mov_b32_e32 v62, v18
	v_mov_b32_e32 v63, v18
	v_mov_b32_e32 v64, v18
	v_mov_b32_e32 v65, v18
	v_mov_b32_e32 v22, v18
	v_mov_b32_e32 v23, v18
	v_mov_b32_e32 v24, v18
	v_mov_b32_e32 v25, v18
	v_mov_b32_e32 v26, v18
	v_mov_b32_e32 v27, v18
	v_mov_b32_e32 v28, v18
	v_mov_b32_e32 v29, v18
	v_mov_b32_e32 v82, v18
	v_mov_b32_e32 v83, v18
	v_mov_b32_e32 v84, v18
	v_mov_b32_e32 v85, v18
	v_mov_b32_e32 v110, v18
	v_mov_b32_e32 v111, v18
	v_mov_b32_e32 v112, v18
	v_mov_b32_e32 v113, v18
	v_mov_b32_e32 v94, v18
	v_mov_b32_e32 v95, v18
	v_mov_b32_e32 v96, v18
	v_mov_b32_e32 v97, v18
	v_mov_b32_e32 v114, v18
	v_mov_b32_e32 v115, v18
	v_mov_b32_e32 v116, v18
	v_mov_b32_e32 v117, v18
	v_mov_b32_e32 v98, v18
	v_mov_b32_e32 v99, v18
	v_mov_b32_e32 v100, v18
	v_mov_b32_e32 v101, v18
	v_mov_b32_e32 v118, v18
	v_mov_b32_e32 v119, v18
	v_mov_b32_e32 v120, v18
	v_mov_b32_e32 v121, v18
	v_mov_b32_e32 v74, v18
	v_mov_b32_e32 v75, v18
	v_mov_b32_e32 v76, v18
	v_mov_b32_e32 v77, v18
	v_mov_b32_e32 v78, v18
	v_mov_b32_e32 v79, v18
	v_mov_b32_e32 v80, v18
	v_mov_b32_e32 v81, v18
	v_mov_b32_e32 v66, v18
	v_mov_b32_e32 v67, v18
	v_mov_b32_e32 v68, v18
	v_mov_b32_e32 v69, v18
	v_mov_b32_e32 v70, v18
	v_mov_b32_e32 v71, v18
	v_mov_b32_e32 v72, v18
	v_mov_b32_e32 v73, v18
	v_mov_b32_e32 v102, v18
	v_mov_b32_e32 v103, v18
	v_mov_b32_e32 v104, v18
	v_mov_b32_e32 v105, v18
	v_mov_b32_e32 v122, v18
	v_mov_b32_e32 v123, v18
	v_mov_b32_e32 v124, v18
	v_mov_b32_e32 v125, v18
	v_mov_b32_e32 v106, v18
	v_mov_b32_e32 v107, v18
	v_mov_b32_e32 v108, v18
	v_mov_b32_e32 v109, v18
	v_mov_b32_e32 v126, v18
	v_mov_b32_e32 v127, v18
	v_mov_b32_e32 v128, v18
	v_mov_b32_e32 v129, v18
	v_mov_b32_e32 v86, v18
	v_mov_b32_e32 v87, v18
	v_mov_b32_e32 v88, v18
	v_mov_b32_e32 v89, v18
	v_mov_b32_e32 v90, v18
	v_mov_b32_e32 v91, v18
	v_mov_b32_e32 v92, v18
	v_mov_b32_e32 v93, v18
	.p2align	6
